# non-temporal hints also on decode state loads/stores, f32 weight conversion loads (P1 tail, P3), P15 row loads and final output stores
# speedup vs baseline: 1.0186x; 1.0040x over previous
.LBB0_142:
	s_add_i32 s3, s56, 0xfffffe00
	s_cmpk_gt_i32 s3, 0xff
	s_mov_b64 s[0:1], -1
	s_cbranch_scc0 .LBB0_170
	s_cmpk_gt_u32 s3, 0x1ff
	s_cbranch_scc0 .LBB0_164
	s_cmpk_gt_u32 s3, 0x2ff
	s_cbranch_scc0 .LBB0_158
	s_cmpk_gt_u32 s3, 0x33f
	s_cbranch_scc0 .LBB0_152
	s_add_i32 s4, s56, 0xfffffac0
	s_cmpk_gt_u32 s4, 0x15ff
	s_cbranch_scc1 .LBB0_151
	s_lshl_b32 s0, s3, 7
	s_mov_b64 s[6:7], s[16:17]
	v_readlane_b32 s12, v242, 0
	s_and_b32 s0, s0, 0x1f80
	v_readlane_b32 s18, v242, 6
	v_readlane_b32 s19, v242, 7
	s_add_u32 s0, s18, s0
	v_and_b32_e32 v38, 7, v143
	s_addc_u32 s1, s19, 0
	v_lshlrev_b32_e32 v34, 4, v38
	v_mov_b32_e32 v35, 0
	v_lshrrev_b32_e32 v1, 3, v142
	v_lshl_add_u64 v[2:3], s[0:1], 0, v[34:35]
	s_and_b32 s0, s4, 0x1fc0
	v_or_b32_e32 v4, s0, v1
	v_lshlrev_b32_e32 v4, 13, v4
	v_mov_b32_e32 v5, v35
	s_waitcnt vmcnt(0)
	v_lshl_add_u64 v[26:27], v[2:3], 0, v[4:5]
	s_mov_b32 s0, 0x10000
	v_add_co_u32_e32 v6, vcc, s0, v26
	s_mov_b32 s0, 0x20000
	s_nop 0
	v_addc_co_u32_e32 v7, vcc, 0, v27, vcc
	v_add_co_u32_e32 v10, vcc, s0, v26
	s_mov_b32 s0, 0x30000
	s_nop 0
	v_addc_co_u32_e32 v11, vcc, 0, v27, vcc
	v_add_co_u32_e32 v14, vcc, s0, v26
	s_mov_b32 s0, 0x40000
	s_nop 0
	v_addc_co_u32_e32 v15, vcc, 0, v27, vcc
	v_add_co_u32_e32 v18, vcc, s0, v26
	s_mov_b32 s0, 0x50000
	s_nop 0
	v_addc_co_u32_e32 v19, vcc, 0, v27, vcc
	v_add_co_u32_e32 v22, vcc, s0, v26
	s_mov_b32 s0, 0x60000
	s_nop 0
	v_addc_co_u32_e32 v23, vcc, 0, v27, vcc
	v_add_co_u32_e32 v28, vcc, s0, v26
	s_mov_b32 s0, 0x70000
	s_nop 0
	v_addc_co_u32_e32 v29, vcc, 0, v27, vcc
	v_add_co_u32_e32 v30, vcc, s0, v26
	global_load_dwordx4 v[2:5], v[26:27], off nt
	s_nop 0
	global_load_dwordx4 v[6:9], v[6:7], off nt
	v_addc_co_u32_e32 v31, vcc, 0, v27, vcc
	global_load_dwordx4 v[10:13], v[10:11], off nt
	s_nop 0
	global_load_dwordx4 v[14:17], v[14:15], off nt
	s_nop 0
	global_load_dwordx4 v[18:21], v[18:19], off nt
	s_nop 0
	global_load_dwordx4 v[22:25], v[22:23], off nt
	s_nop 0
	global_load_dwordx4 v[26:29], v[28:29], off nt
	s_nop 0
	global_load_dwordx4 v[30:33], v[30:31], off nt
	v_readlane_b32 s0, v242, 29
	v_lshl_add_u64 v[36:37], s[18:19], 0, v[34:35]
	v_mul_u32_u24_e32 v40, 0x420, v38
	v_add_u32_e32 v44, s0, v34
	v_lshl_add_u64 v[38:39], s[92:93], 0, v[34:35]
	v_lshlrev_b32_e32 v34, 2, v1
	v_readlane_b32 s16, v242, 4
	v_readlane_b32 s17, v242, 5
	v_add3_u32 v40, s0, v40, v34
	v_mul_u32_u24_e32 v34, 0x84, v1
	s_mov_b64 s[16:17], s[6:7]
	s_mov_b32 s1, 0
	v_or_b32_e32 v41, 8, v1
	v_or_b32_e32 v42, 16, v1
	v_or_b32_e32 v43, 24, v1
	s_add_i32 s0, s56, 0xfffff800
	s_lshl_b32 s6, s4, 5
	v_add_u32_e32 v44, v44, v34
	v_readlane_b32 s13, v242, 1
	v_readlane_b32 s14, v242, 2
	v_readlane_b32 s15, v242, 3
	s_branch .LBB0_149

.LBB0_149:
	v_add_u32_e32 v34, 0x420, v44
	s_waitcnt vmcnt(7)
	ds_write2_b32 v44, v2, v3 offset1:1
	ds_write2_b32 v44, v4, v5 offset0:2 offset1:3
	s_waitcnt vmcnt(6)
	ds_write2_b32 v34, v6, v7 offset1:1
	v_add_u32_e32 v34, 0x428, v44
	ds_write2_b32 v34, v8, v9 offset1:1
	v_add_u32_e32 v34, 0x840, v44
	s_waitcnt vmcnt(5)
	ds_write2_b32 v34, v10, v11 offset1:1
	v_add_u32_e32 v34, 0x848, v44
	ds_write2_b32 v34, v12, v13 offset1:1
	v_add_u32_e32 v34, 0xc60, v44
	s_waitcnt vmcnt(4)
	ds_write2_b32 v34, v14, v15 offset1:1
	v_add_u32_e32 v34, 0xc68, v44
	ds_write2_b32 v34, v16, v17 offset1:1
	v_add_u32_e32 v34, 0x1080, v44
	s_waitcnt vmcnt(3)
	ds_write2_b32 v34, v18, v19 offset1:1
	v_add_u32_e32 v34, 0x1088, v44
	ds_write2_b32 v34, v20, v21 offset1:1
	v_add_u32_e32 v34, 0x14a0, v44
	s_waitcnt vmcnt(2)
	ds_write2_b32 v34, v22, v23 offset1:1
	v_add_u32_e32 v34, 0x14a8, v44
	s_add_i32 s7, s0, 0x2c0
	ds_write2_b32 v34, v24, v25 offset1:1
	v_add_u32_e32 v34, 0x18c0, v44
	s_and_b32 s10, s6, 0x7e0
	s_waitcnt vmcnt(1)
	ds_write2_b32 v34, v26, v27 offset1:1
	v_add_u32_e32 v34, 0x18c8, v44
	s_cmpk_gt_i32 s7, 0x133f
	ds_write2_b32 v34, v28, v29 offset1:1
	v_add_u32_e32 v34, 0x1ce0, v44
	s_cselect_b64 s[4:5], -1, 0
	s_waitcnt vmcnt(0)
	ds_write2_b32 v34, v30, v31 offset1:1
	v_add_u32_e32 v34, 0x1ce8, v44
	s_and_b64 vcc, exec, s[4:5]
	ds_write2_b32 v34, v32, v33 offset1:1
	s_cbranch_vccnz .LBB0_148
	s_addk_i32 s0, 0x580
	s_and_b32 s0, s0, 0x7fffffc0
	v_or_b32_e32 v34, s0, v1
	s_lshl_b32 s0, s10, 2
	v_lshlrev_b64 v[2:3], 13, v[34:35]
	v_or_b32_e32 v4, 8, v34
	v_mov_b32_e32 v5, v35
	v_or_b32_e32 v10, 16, v34
	v_mov_b32_e32 v11, v35
	v_or_b32_e32 v12, 24, v34
	v_mov_b32_e32 v13, v35
	v_or_b32_e32 v18, 32, v34
	v_mov_b32_e32 v19, v35
	v_or_b32_e32 v20, 40, v34
	v_mov_b32_e32 v21, v35
	v_or_b32_e32 v28, 48, v34
	v_mov_b32_e32 v29, v35
	v_or_b32_e32 v34, 56, v34
	v_lshl_add_u64 v[26:27], v[36:37], 0, s[0:1]
	v_lshlrev_b64 v[4:5], 13, v[4:5]
	v_lshlrev_b64 v[10:11], 13, v[10:11]
	v_lshlrev_b64 v[12:13], 13, v[12:13]
	v_lshlrev_b64 v[18:19], 13, v[18:19]
	v_lshlrev_b64 v[20:21], 13, v[20:21]
	v_lshlrev_b64 v[28:29], 13, v[28:29]
	v_lshlrev_b64 v[30:31], 13, v[34:35]
	v_lshl_add_u64 v[2:3], v[26:27], 0, v[2:3]
	v_lshl_add_u64 v[6:7], v[26:27], 0, v[4:5]
	v_lshl_add_u64 v[10:11], v[26:27], 0, v[10:11]
	v_lshl_add_u64 v[14:15], v[26:27], 0, v[12:13]
	v_lshl_add_u64 v[18:19], v[26:27], 0, v[18:19]
	v_lshl_add_u64 v[22:23], v[26:27], 0, v[20:21]
	v_lshl_add_u64 v[28:29], v[26:27], 0, v[28:29]
	v_lshl_add_u64 v[30:31], v[26:27], 0, v[30:31]
	global_load_dwordx4 v[2:5], v[2:3], off nt
	s_nop 0
	global_load_dwordx4 v[6:9], v[6:7], off nt
	s_nop 0
	global_load_dwordx4 v[10:13], v[10:11], off nt
	s_nop 0
	global_load_dwordx4 v[14:17], v[14:15], off nt
	s_nop 0
	global_load_dwordx4 v[18:21], v[18:19], off nt
	s_nop 0
	global_load_dwordx4 v[22:25], v[22:23], off nt
	s_nop 0
	global_load_dwordx4 v[26:29], v[28:29], off nt
	s_nop 0
	global_load_dwordx4 v[30:33], v[30:31], off nt
	s_branch .LBB0_148

.LBB0_152:
	s_andn2_b64 vcc, exec, s[0:1]
	s_cbranch_vccnz .LBB0_157
	v_readlane_b32 s40, v242, 12
	v_readlane_b32 s44, v242, 16
	v_readlane_b32 s45, v242, 17
	v_readlane_b32 s46, v242, 18
	v_readlane_b32 s47, v242, 19
	v_readlane_b32 s48, v242, 20
	v_readlane_b32 s49, v242, 21
	v_readlane_b32 s50, v242, 22
	v_readlane_b32 s51, v242, 23
	s_lshl_b32 s0, s3, 7
	v_readlane_b32 s52, v242, 24
	v_readlane_b32 s53, v242, 25
	v_readlane_b32 s54, v242, 26
	v_readlane_b32 s55, v242, 27
	s_mov_b64 s[44:45], s[48:49]
	s_add_i32 s4, s56, 0xfffffb00
	s_and_b32 s0, s0, 0x780
	s_mov_b64 s[46:47], s[50:51]
	s_mov_b64 s[48:49], s[52:53]
	s_add_u32 s0, s48, s0
	v_and_b32_e32 v38, 7, v143
	s_addc_u32 s1, s49, 0
	v_lshlrev_b32_e32 v36, 4, v38
	v_mov_b32_e32 v37, 0
	s_waitcnt vmcnt(0)
	v_lshl_add_u64 v[2:3], s[0:1], 0, v[36:37]
	s_lshl_b32 s0, s3, 2
	v_lshrrev_b32_e32 v1, 3, v142
	s_and_b32 s0, s0, 0x3c0
	v_or_b32_e32 v4, s0, v1
	v_lshlrev_b32_e32 v4, 11, v4
	v_mov_b32_e32 v5, v37
	v_lshl_add_u64 v[26:27], v[2:3], 0, v[4:5]
	s_movk_i32 s0, 0x4000
	v_add_co_u32_e32 v6, vcc, s0, v26
	s_mov_b32 s0, 0x8000
	s_nop 0
	v_addc_co_u32_e32 v7, vcc, 0, v27, vcc
	v_add_co_u32_e32 v10, vcc, s0, v26
	s_mov_b32 s0, 0xc000
	s_nop 0
	v_addc_co_u32_e32 v11, vcc, 0, v27, vcc
	v_add_co_u32_e32 v14, vcc, s0, v26
	s_mov_b32 s0, 0x10000
	s_nop 0
	v_addc_co_u32_e32 v15, vcc, 0, v27, vcc
	v_add_co_u32_e32 v18, vcc, s0, v26
	s_mov_b32 s0, 0x14000
	s_nop 0
	v_addc_co_u32_e32 v19, vcc, 0, v27, vcc
	v_add_co_u32_e32 v22, vcc, s0, v26
	s_mov_b32 s0, 0x18000
	s_nop 0
	v_addc_co_u32_e32 v23, vcc, 0, v27, vcc
	v_add_co_u32_e32 v28, vcc, s0, v26
	s_mov_b32 s0, 0x1c000
	s_nop 0
	v_addc_co_u32_e32 v29, vcc, 0, v27, vcc
	v_add_co_u32_e32 v30, vcc, s0, v26
	global_load_dwordx4 v[2:5], v[26:27], off nt
	s_nop 0
	global_load_dwordx4 v[6:9], v[6:7], off nt
	v_addc_co_u32_e32 v31, vcc, 0, v27, vcc
	global_load_dwordx4 v[10:13], v[10:11], off nt
	s_nop 0
	global_load_dwordx4 v[14:17], v[14:15], off nt
	s_nop 0
	global_load_dwordx4 v[18:21], v[18:19], off nt
	s_nop 0
	global_load_dwordx4 v[22:25], v[22:23], off nt
	s_nop 0
	global_load_dwordx4 v[26:29], v[28:29], off nt
	s_nop 0
	global_load_dwordx4 v[30:33], v[30:31], off nt
	v_readlane_b32 s0, v242, 29
	v_mul_u32_u24_e32 v38, 0x420, v38
	v_lshlrev_b32_e32 v40, 2, v1
	v_add_u32_e32 v39, s0, v36
	v_add3_u32 v38, s0, v38, v40
	v_mul_u32_u24_e32 v40, 0x84, v1
	s_lshl_b32 s0, s4, 5
	v_lshl_add_u64 v[34:35], s[48:49], 0, v[36:37]
	v_lshl_add_u64 v[36:37], s[16:17], 0, v[36:37]
	s_add_i32 s5, s0, 0x800
	v_add_u32_e32 v39, v39, v40
	v_readlane_b32 s41, v242, 13
	v_readlane_b32 s42, v242, 14
	v_readlane_b32 s43, v242, 15
	s_mov_b64 s[50:51], s[54:55]
	s_branch .LBB0_155

.LBB0_155:
	v_add_u32_e32 v40, 0x420, v39
	s_waitcnt vmcnt(7)
	ds_write2_b32 v39, v2, v3 offset1:1
	ds_write2_b32 v39, v4, v5 offset0:2 offset1:3
	s_waitcnt vmcnt(6)
	ds_write2_b32 v40, v6, v7 offset1:1
	v_add_u32_e32 v40, 0x428, v39
	ds_write2_b32 v40, v8, v9 offset1:1
	v_add_u32_e32 v40, 0x840, v39
	s_waitcnt vmcnt(5)
	ds_write2_b32 v40, v10, v11 offset1:1
	v_add_u32_e32 v40, 0x848, v39
	ds_write2_b32 v40, v12, v13 offset1:1
	v_add_u32_e32 v40, 0xc60, v39
	s_waitcnt vmcnt(4)
	ds_write2_b32 v40, v14, v15 offset1:1
	v_add_u32_e32 v40, 0xc68, v39
	ds_write2_b32 v40, v16, v17 offset1:1
	v_add_u32_e32 v40, 0x1080, v39
	s_waitcnt vmcnt(3)
	ds_write2_b32 v40, v18, v19 offset1:1
	v_add_u32_e32 v40, 0x1088, v39
	ds_write2_b32 v40, v20, v21 offset1:1
	v_add_u32_e32 v40, 0x14a0, v39
	s_waitcnt vmcnt(2)
	ds_write2_b32 v40, v22, v23 offset1:1
	v_add_u32_e32 v40, 0x14a8, v39
	ds_write2_b32 v40, v24, v25 offset1:1
	v_add_u32_e32 v40, 0x18c0, v39
	s_add_i32 s6, s4, 64
	s_waitcnt vmcnt(1)
	ds_write2_b32 v40, v26, v27 offset1:1
	v_add_u32_e32 v40, 0x18c8, v39
	s_cmpk_gt_i32 s4, 0x1bf
	ds_write2_b32 v40, v28, v29 offset1:1
	v_add_u32_e32 v40, 0x1ce0, v39
	s_cselect_b64 s[0:1], -1, 0
	s_waitcnt vmcnt(0)
	ds_write2_b32 v40, v30, v31 offset1:1
	v_add_u32_e32 v40, 0x1ce8, v39
	s_and_b64 vcc, exec, s[0:1]
	ds_write2_b32 v40, v32, v33 offset1:1
	s_cbranch_vccnz .LBB0_154
	s_ashr_i32 s7, s6, 31
	s_lshr_b32 s7, s7, 28
	s_add_i32 s7, s6, s7
	s_ashr_i32 s7, s7, 4
	v_lshl_or_b32 v26, s7, 6, v1
	s_lshl_b32 s10, s7, 9
	v_ashrrev_i32_e32 v27, 31, v26
	s_sub_i32 s10, s5, s10
	v_lshlrev_b64 v[2:3], 11, v[26:27]
	v_or_b32_e32 v4, 8, v26
	v_or_b32_e32 v10, 16, v26
	v_or_b32_e32 v12, 24, v26
	v_or_b32_e32 v18, 32, v26
	v_or_b32_e32 v20, 40, v26
	v_or_b32_e32 v30, 48, v26
	v_or_b32_e32 v26, 56, v26
	s_ashr_i32 s11, s10, 31
	v_ashrrev_i32_e32 v5, 31, v4
	v_ashrrev_i32_e32 v11, 31, v10
	v_ashrrev_i32_e32 v13, 31, v12
	v_ashrrev_i32_e32 v19, 31, v18
	v_ashrrev_i32_e32 v21, 31, v20
	v_ashrrev_i32_e32 v31, 31, v30
	v_ashrrev_i32_e32 v27, 31, v26
	v_lshl_add_u64 v[28:29], s[10:11], 2, v[34:35]
	v_lshlrev_b64 v[4:5], 11, v[4:5]
	v_lshlrev_b64 v[10:11], 11, v[10:11]
	v_lshlrev_b64 v[12:13], 11, v[12:13]
	v_lshlrev_b64 v[18:19], 11, v[18:19]
	v_lshlrev_b64 v[20:21], 11, v[20:21]
	v_lshlrev_b64 v[30:31], 11, v[30:31]
	v_lshlrev_b64 v[26:27], 11, v[26:27]
	v_lshl_add_u64 v[2:3], v[28:29], 0, v[2:3]
	v_lshl_add_u64 v[6:7], v[28:29], 0, v[4:5]
	v_lshl_add_u64 v[10:11], v[28:29], 0, v[10:11]
	v_lshl_add_u64 v[14:15], v[28:29], 0, v[12:13]
	v_lshl_add_u64 v[18:19], v[28:29], 0, v[18:19]
	v_lshl_add_u64 v[22:23], v[28:29], 0, v[20:21]
	v_lshl_add_u64 v[30:31], v[28:29], 0, v[30:31]
	v_lshl_add_u64 v[32:33], v[28:29], 0, v[26:27]
	global_load_dwordx4 v[2:5], v[2:3], off nt
	s_nop 0
	global_load_dwordx4 v[6:9], v[6:7], off nt
	s_nop 0
	global_load_dwordx4 v[10:13], v[10:11], off nt
	s_nop 0
	global_load_dwordx4 v[14:17], v[14:15], off nt
	s_nop 0
	global_load_dwordx4 v[18:21], v[18:19], off nt
	s_nop 0
	global_load_dwordx4 v[22:25], v[22:23], off nt
	s_nop 0
	global_load_dwordx4 v[26:29], v[30:31], off nt
	s_nop 0
	global_load_dwordx4 v[30:33], v[32:33], off nt
	s_branch .LBB0_154

.LBB0_158:
	s_andn2_b64 vcc, exec, s[0:1]
	s_cbranch_vccnz .LBB0_163
	s_lshl_b32 s0, s3, 7
	s_mov_b64 s[6:7], s[16:17]
	v_readlane_b32 s12, v242, 0
	s_add_i32 s4, s56, 0xfffffc00
	s_and_b32 s0, s0, 0x1f80
	v_readlane_b32 s14, v242, 2
	v_readlane_b32 s15, v242, 3
	s_add_u32 s0, s14, s0
	v_and_b32_e32 v38, 7, v143
	s_addc_u32 s1, s15, 0
	v_lshlrev_b32_e32 v36, 4, v38
	v_mov_b32_e32 v37, 0
	v_lshrrev_b32_e32 v1, 3, v142
	s_waitcnt vmcnt(0)
	v_lshl_add_u64 v[2:3], s[0:1], 0, v[36:37]
	s_and_b32 s0, s56, 0xc0
	v_or_b32_e32 v4, s0, v1
	v_lshlrev_b32_e32 v4, 13, v4
	v_mov_b32_e32 v5, v37
	v_lshl_add_u64 v[26:27], v[2:3], 0, v[4:5]
	s_mov_b32 s0, 0x10000
	v_add_co_u32_e32 v6, vcc, s0, v26
	s_mov_b32 s0, 0x20000
	s_nop 0
	v_addc_co_u32_e32 v7, vcc, 0, v27, vcc
	v_add_co_u32_e32 v10, vcc, s0, v26
	s_mov_b32 s0, 0x30000
	s_nop 0
	v_addc_co_u32_e32 v11, vcc, 0, v27, vcc
	v_add_co_u32_e32 v14, vcc, s0, v26
	s_mov_b32 s0, 0x40000
	s_nop 0
	v_addc_co_u32_e32 v15, vcc, 0, v27, vcc
	v_add_co_u32_e32 v18, vcc, s0, v26
	s_mov_b32 s0, 0x50000
	s_nop 0
	v_addc_co_u32_e32 v19, vcc, 0, v27, vcc
	v_add_co_u32_e32 v22, vcc, s0, v26
	s_mov_b32 s0, 0x60000
	s_nop 0
	v_addc_co_u32_e32 v23, vcc, 0, v27, vcc
	v_add_co_u32_e32 v28, vcc, s0, v26
	s_mov_b32 s0, 0x70000
	s_nop 0
	v_addc_co_u32_e32 v29, vcc, 0, v27, vcc
	v_add_co_u32_e32 v30, vcc, s0, v26
	global_load_dwordx4 v[2:5], v[26:27], off nt
	s_nop 0
	global_load_dwordx4 v[6:9], v[6:7], off nt
	v_addc_co_u32_e32 v31, vcc, 0, v27, vcc
	global_load_dwordx4 v[10:13], v[10:11], off nt
	s_nop 0
	global_load_dwordx4 v[14:17], v[14:15], off nt
	s_nop 0
	global_load_dwordx4 v[18:21], v[18:19], off nt
	s_nop 0
	global_load_dwordx4 v[22:25], v[22:23], off nt
	s_nop 0
	global_load_dwordx4 v[26:29], v[28:29], off nt
	s_nop 0
	global_load_dwordx4 v[30:33], v[30:31], off nt
	v_readlane_b32 s0, v242, 49
	v_readlane_b32 s5, v242, 29
	v_mul_u32_u24_e32 v38, 0x420, v38
	v_readlane_b32 s1, v242, 50
	v_lshlrev_b32_e32 v40, 2, v1
	v_readlane_b32 s16, v242, 4
	v_readlane_b32 s17, v242, 5
	v_add_u32_e32 v39, s5, v36
	v_lshl_add_u64 v[34:35], s[14:15], 0, v[36:37]
	v_lshl_add_u64 v[36:37], s[0:1], 0, v[36:37]
	v_add3_u32 v38, s5, v38, v40
	v_mul_u32_u24_e32 v40, 0x84, v1
	s_lshl_b32 s0, s4, 5
	s_mov_b64 s[16:17], s[6:7]
	s_add_i32 s5, s0, 0x2000
	v_add_u32_e32 v39, v39, v40
	v_readlane_b32 s13, v242, 1
	v_readlane_b32 s18, v242, 6
	v_readlane_b32 s19, v242, 7
	s_branch .LBB0_161

.LBB0_161:
	v_add_u32_e32 v40, 0x420, v39
	s_waitcnt vmcnt(7)
	ds_write2_b32 v39, v2, v3 offset1:1
	ds_write2_b32 v39, v4, v5 offset0:2 offset1:3
	s_waitcnt vmcnt(6)
	ds_write2_b32 v40, v6, v7 offset1:1
	v_add_u32_e32 v40, 0x428, v39
	ds_write2_b32 v40, v8, v9 offset1:1
	v_add_u32_e32 v40, 0x840, v39
	s_waitcnt vmcnt(5)
	ds_write2_b32 v40, v10, v11 offset1:1
	v_add_u32_e32 v40, 0x848, v39
	ds_write2_b32 v40, v12, v13 offset1:1
	v_add_u32_e32 v40, 0xc60, v39
	s_waitcnt vmcnt(4)
	ds_write2_b32 v40, v14, v15 offset1:1
	v_add_u32_e32 v40, 0xc68, v39
	ds_write2_b32 v40, v16, v17 offset1:1
	v_add_u32_e32 v40, 0x1080, v39
	s_waitcnt vmcnt(3)
	ds_write2_b32 v40, v18, v19 offset1:1
	v_add_u32_e32 v40, 0x1088, v39
	ds_write2_b32 v40, v20, v21 offset1:1
	v_add_u32_e32 v40, 0x14a0, v39
	s_waitcnt vmcnt(2)
	ds_write2_b32 v40, v22, v23 offset1:1
	v_add_u32_e32 v40, 0x14a8, v39
	ds_write2_b32 v40, v24, v25 offset1:1
	v_add_u32_e32 v40, 0x18c0, v39
	s_add_i32 s6, s4, 0x100
	s_waitcnt vmcnt(1)
	ds_write2_b32 v40, v26, v27 offset1:1
	v_add_u32_e32 v40, 0x18c8, v39
	s_cmpk_gt_i32 s4, 0x6ff
	ds_write2_b32 v40, v28, v29 offset1:1
	v_add_u32_e32 v40, 0x1ce0, v39
	s_cselect_b64 s[0:1], -1, 0
	s_waitcnt vmcnt(0)
	ds_write2_b32 v40, v30, v31 offset1:1
	v_add_u32_e32 v40, 0x1ce8, v39
	s_and_b64 vcc, exec, s[0:1]
	ds_write2_b32 v40, v32, v33 offset1:1
	s_cbranch_vccnz .LBB0_160
	s_ashr_i32 s7, s6, 31
	s_lshr_b32 s7, s7, 26
	s_add_i32 s7, s6, s7
	s_and_b32 s11, s7, 0xffffffc0
	s_lshl_b32 s7, s7, 5
	v_or_b32_e32 v26, s11, v1
	s_and_b32 s7, s7, 0xfffff800
	v_ashrrev_i32_e32 v27, 31, v26
	s_sub_i32 s10, s5, s7
	v_lshlrev_b64 v[2:3], 13, v[26:27]
	v_or_b32_e32 v4, 8, v26
	v_or_b32_e32 v10, 16, v26
	v_or_b32_e32 v12, 24, v26
	v_or_b32_e32 v18, 32, v26
	v_or_b32_e32 v20, 40, v26
	v_or_b32_e32 v30, 48, v26
	v_or_b32_e32 v26, 56, v26
	s_ashr_i32 s11, s10, 31
	v_ashrrev_i32_e32 v5, 31, v4
	v_ashrrev_i32_e32 v11, 31, v10
	v_ashrrev_i32_e32 v13, 31, v12
	v_ashrrev_i32_e32 v19, 31, v18
	v_ashrrev_i32_e32 v21, 31, v20
	v_ashrrev_i32_e32 v31, 31, v30
	v_ashrrev_i32_e32 v27, 31, v26
	v_lshl_add_u64 v[28:29], s[10:11], 2, v[34:35]
	v_lshlrev_b64 v[4:5], 13, v[4:5]
	v_lshlrev_b64 v[10:11], 13, v[10:11]
	v_lshlrev_b64 v[12:13], 13, v[12:13]
	v_lshlrev_b64 v[18:19], 13, v[18:19]
	v_lshlrev_b64 v[20:21], 13, v[20:21]
	v_lshlrev_b64 v[30:31], 13, v[30:31]
	v_lshlrev_b64 v[26:27], 13, v[26:27]
	v_lshl_add_u64 v[2:3], v[28:29], 0, v[2:3]
	v_lshl_add_u64 v[6:7], v[28:29], 0, v[4:5]
	v_lshl_add_u64 v[10:11], v[28:29], 0, v[10:11]
	v_lshl_add_u64 v[14:15], v[28:29], 0, v[12:13]
	v_lshl_add_u64 v[18:19], v[28:29], 0, v[18:19]
	v_lshl_add_u64 v[22:23], v[28:29], 0, v[20:21]
	v_lshl_add_u64 v[30:31], v[28:29], 0, v[30:31]
	v_lshl_add_u64 v[32:33], v[28:29], 0, v[26:27]
	global_load_dwordx4 v[2:5], v[2:3], off nt
	s_nop 0
	global_load_dwordx4 v[6:9], v[6:7], off nt
	s_nop 0
	global_load_dwordx4 v[10:13], v[10:11], off nt
	s_nop 0
	global_load_dwordx4 v[14:17], v[14:15], off nt
	s_nop 0
	global_load_dwordx4 v[18:21], v[18:19], off nt
	s_nop 0
	global_load_dwordx4 v[22:25], v[22:23], off nt
	s_nop 0
	global_load_dwordx4 v[26:29], v[30:31], off nt
	s_nop 0
	global_load_dwordx4 v[30:33], v[32:33], off nt
	s_branch .LBB0_160

.LBB0_164:
	s_andn2_b64 vcc, exec, s[0:1]
	s_cbranch_vccnz .LBB0_169
	v_readlane_b32 s40, v242, 12
	s_lshl_b32 s0, s3, 7
	v_readlane_b32 s50, v242, 22
	v_readlane_b32 s51, v242, 23
	v_readlane_b32 s54, v242, 26
	v_readlane_b32 s55, v242, 27
	s_add_i32 s4, s56, 0xfffffd00
	s_and_b32 s0, s0, 0x1f80
	s_mov_b64 s[50:51], s[54:55]
	s_add_u32 s0, s50, s0
	v_and_b32_e32 v38, 7, v143
	s_addc_u32 s1, s51, 0
	v_lshlrev_b32_e32 v36, 4, v38
	v_mov_b32_e32 v37, 0
	v_lshrrev_b32_e32 v1, 3, v142
	s_waitcnt vmcnt(0)
	v_lshl_add_u64 v[2:3], s[0:1], 0, v[36:37]
	s_and_b32 s0, s56, 0xc0
	v_or_b32_e32 v4, s0, v1
	v_lshlrev_b32_e32 v4, 13, v4
	v_mov_b32_e32 v5, v37
	v_lshl_add_u64 v[26:27], v[2:3], 0, v[4:5]
	s_mov_b32 s0, 0x10000
	v_add_co_u32_e32 v6, vcc, s0, v26
	s_mov_b32 s0, 0x20000
	s_nop 0
	v_addc_co_u32_e32 v7, vcc, 0, v27, vcc
	v_add_co_u32_e32 v10, vcc, s0, v26
	s_mov_b32 s0, 0x30000
	s_nop 0
	v_addc_co_u32_e32 v11, vcc, 0, v27, vcc
	v_add_co_u32_e32 v14, vcc, s0, v26
	s_mov_b32 s0, 0x40000
	s_nop 0
	v_addc_co_u32_e32 v15, vcc, 0, v27, vcc
	v_add_co_u32_e32 v18, vcc, s0, v26
	s_mov_b32 s0, 0x50000
	s_nop 0
	v_addc_co_u32_e32 v19, vcc, 0, v27, vcc
	v_add_co_u32_e32 v22, vcc, s0, v26
	s_mov_b32 s0, 0x60000
	s_nop 0
	v_addc_co_u32_e32 v23, vcc, 0, v27, vcc
	v_add_co_u32_e32 v28, vcc, s0, v26
	s_mov_b32 s0, 0x70000
	s_nop 0
	v_addc_co_u32_e32 v29, vcc, 0, v27, vcc
	v_add_co_u32_e32 v30, vcc, s0, v26
	global_load_dwordx4 v[2:5], v[26:27], off nt
	s_nop 0
	global_load_dwordx4 v[6:9], v[6:7], off nt
	v_addc_co_u32_e32 v31, vcc, 0, v27, vcc
	global_load_dwordx4 v[10:13], v[10:11], off nt
	s_nop 0
	global_load_dwordx4 v[14:17], v[14:15], off nt
	s_nop 0
	global_load_dwordx4 v[18:21], v[18:19], off nt
	s_nop 0
	global_load_dwordx4 v[22:25], v[22:23], off nt
	s_nop 0
	global_load_dwordx4 v[26:29], v[28:29], off nt
	s_nop 0
	global_load_dwordx4 v[30:33], v[30:31], off nt
	v_readlane_b32 s0, v242, 29
	v_mul_u32_u24_e32 v38, 0x420, v38
	v_readlane_b32 s6, v242, 47
	v_lshlrev_b32_e32 v40, 2, v1
	v_add_u32_e32 v39, s0, v36
	v_readlane_b32 s7, v242, 48
	v_add3_u32 v38, s0, v38, v40
	v_mul_u32_u24_e32 v40, 0x84, v1
	s_lshl_b32 s0, s4, 5
	v_lshl_add_u64 v[34:35], s[50:51], 0, v[36:37]
	v_lshl_add_u64 v[36:37], s[6:7], 0, v[36:37]
	s_add_i32 s5, s0, 0x2000
	v_add_u32_e32 v39, v39, v40
	v_readlane_b32 s41, v242, 13
	v_readlane_b32 s42, v242, 14
	v_readlane_b32 s43, v242, 15
	v_readlane_b32 s44, v242, 16
	v_readlane_b32 s45, v242, 17
	v_readlane_b32 s46, v242, 18
	v_readlane_b32 s47, v242, 19
	v_readlane_b32 s48, v242, 20
	v_readlane_b32 s49, v242, 21
	v_readlane_b32 s52, v242, 24
	v_readlane_b32 s53, v242, 25
	s_branch .LBB0_167

.LBB0_170:
	s_andn2_b64 vcc, exec, s[0:1]
	s_cbranch_vccnz .LBB0_176
	s_ashr_i32 s0, s3, 31
	s_lshr_b32 s0, s0, 26
	s_add_i32 s0, s3, s0
	s_and_b32 s4, s0, 0xffffffc0
	s_sub_i32 s0, s3, s4
	v_lshrrev_b32_e32 v1, 3, v142
	s_lshl_b32 s0, s0, 5
	v_readlane_b32 s40, v242, 12
	s_ashr_i32 s1, s0, 31
	v_readlane_b32 s44, v242, 16
	v_readlane_b32 s45, v242, 17
	v_readlane_b32 s46, v242, 18
	v_readlane_b32 s47, v242, 19
	v_readlane_b32 s48, v242, 20
	v_readlane_b32 s49, v242, 21
	s_waitcnt vmcnt(0)
	v_or_b32_e32 v28, s4, v1
	s_lshl_b64 s[0:1], s[0:1], 2
	v_readlane_b32 s50, v242, 22
	v_readlane_b32 s51, v242, 23
	s_mov_b64 s[44:45], s[48:49]
	v_ashrrev_i32_e32 v29, 31, v28
	s_add_u32 s0, s44, s0
	v_and_b32_e32 v38, 7, v143
	v_lshlrev_b64 v[2:3], 13, v[28:29]
	v_or_b32_e32 v4, 8, v28
	v_or_b32_e32 v10, 16, v28
	v_or_b32_e32 v12, 24, v28
	v_or_b32_e32 v18, 32, v28
	v_or_b32_e32 v20, 40, v28
	v_or_b32_e32 v30, 48, v28
	v_or_b32_e32 v28, 56, v28
	s_addc_u32 s1, s45, s1
	v_lshlrev_b32_e32 v36, 4, v38
	v_mov_b32_e32 v37, 0
	v_ashrrev_i32_e32 v5, 31, v4
	v_ashrrev_i32_e32 v11, 31, v10
	v_ashrrev_i32_e32 v13, 31, v12
	v_ashrrev_i32_e32 v19, 31, v18
	v_ashrrev_i32_e32 v21, 31, v20
	v_ashrrev_i32_e32 v31, 31, v30
	v_ashrrev_i32_e32 v29, 31, v28
	v_lshl_add_u64 v[26:27], s[0:1], 0, v[36:37]
	v_lshlrev_b64 v[4:5], 13, v[4:5]
	v_lshlrev_b64 v[10:11], 13, v[10:11]
	v_lshlrev_b64 v[12:13], 13, v[12:13]
	v_lshlrev_b64 v[18:19], 13, v[18:19]
	v_lshlrev_b64 v[20:21], 13, v[20:21]
	v_lshlrev_b64 v[30:31], 13, v[30:31]
	v_lshlrev_b64 v[28:29], 13, v[28:29]
	v_lshl_add_u64 v[2:3], v[26:27], 0, v[2:3]
	v_lshl_add_u64 v[6:7], v[26:27], 0, v[4:5]
	v_lshl_add_u64 v[10:11], v[26:27], 0, v[10:11]
	v_lshl_add_u64 v[14:15], v[26:27], 0, v[12:13]
	v_lshl_add_u64 v[18:19], v[26:27], 0, v[18:19]
	v_lshl_add_u64 v[22:23], v[26:27], 0, v[20:21]
	v_lshl_add_u64 v[30:31], v[26:27], 0, v[30:31]
	v_lshl_add_u64 v[32:33], v[26:27], 0, v[28:29]
	global_load_dwordx4 v[2:5], v[2:3], off nt
	s_nop 0
	global_load_dwordx4 v[6:9], v[6:7], off nt
	s_nop 0
	global_load_dwordx4 v[10:13], v[10:11], off nt
	s_nop 0
	global_load_dwordx4 v[14:17], v[14:15], off nt
	s_nop 0
	global_load_dwordx4 v[18:21], v[18:19], off nt
	s_nop 0
	global_load_dwordx4 v[22:25], v[22:23], off nt
	s_nop 0
	global_load_dwordx4 v[26:29], v[30:31], off nt
	s_nop 0
	global_load_dwordx4 v[30:33], v[32:33], off nt
	v_readlane_b32 s0, v242, 29
	v_mul_u32_u24_e32 v38, 0x420, v38
	v_lshlrev_b32_e32 v40, 2, v1
	v_add_u32_e32 v39, s0, v36
	v_add3_u32 v38, s0, v38, v40
	v_mul_u32_u24_e32 v40, 0x84, v1
	s_lshl_b32 s0, s3, 5
	v_lshl_add_u64 v[34:35], s[44:45], 0, v[36:37]
	v_lshl_add_u64 v[36:37], s[20:21], 0, v[36:37]
	s_add_i32 s4, s0, 0x2000
	v_add_u32_e32 v39, v39, v40
	v_readlane_b32 s41, v242, 13
	v_readlane_b32 s42, v242, 14
	v_readlane_b32 s43, v242, 15
	v_readlane_b32 s52, v242, 24
	v_readlane_b32 s53, v242, 25
	v_readlane_b32 s54, v242, 26
	v_readlane_b32 s55, v242, 27
	s_mov_b64 s[46:47], s[50:51]
	s_branch .LBB0_173

.LBB0_173:
	v_add_u32_e32 v40, 0x420, v39
	s_waitcnt vmcnt(7)
	ds_write2_b32 v39, v2, v3 offset1:1
	ds_write2_b32 v39, v4, v5 offset0:2 offset1:3
	s_waitcnt vmcnt(6)
	ds_write2_b32 v40, v6, v7 offset1:1
	v_add_u32_e32 v40, 0x428, v39
	ds_write2_b32 v40, v8, v9 offset1:1
	v_add_u32_e32 v40, 0x840, v39
	s_waitcnt vmcnt(5)
	ds_write2_b32 v40, v10, v11 offset1:1
	v_add_u32_e32 v40, 0x848, v39
	ds_write2_b32 v40, v12, v13 offset1:1
	v_add_u32_e32 v40, 0xc60, v39
	s_waitcnt vmcnt(4)
	ds_write2_b32 v40, v14, v15 offset1:1
	v_add_u32_e32 v40, 0xc68, v39
	ds_write2_b32 v40, v16, v17 offset1:1
	v_add_u32_e32 v40, 0x1080, v39
	s_waitcnt vmcnt(3)
	ds_write2_b32 v40, v18, v19 offset1:1
	v_add_u32_e32 v40, 0x1088, v39
	ds_write2_b32 v40, v20, v21 offset1:1
	v_add_u32_e32 v40, 0x14a0, v39
	s_waitcnt vmcnt(2)
	ds_write2_b32 v40, v22, v23 offset1:1
	v_add_u32_e32 v40, 0x14a8, v39
	ds_write2_b32 v40, v24, v25 offset1:1
	v_add_u32_e32 v40, 0x18c0, v39
	s_add_i32 s5, s3, 0x100
	s_waitcnt vmcnt(1)
	ds_write2_b32 v40, v26, v27 offset1:1
	v_add_u32_e32 v40, 0x18c8, v39
	s_cmpk_gt_i32 s3, 0x6ff
	ds_write2_b32 v40, v28, v29 offset1:1
	v_add_u32_e32 v40, 0x1ce0, v39
	s_cselect_b64 s[0:1], -1, 0
	s_waitcnt vmcnt(0)
	ds_write2_b32 v40, v30, v31 offset1:1
	v_add_u32_e32 v40, 0x1ce8, v39
	s_and_b64 vcc, exec, s[0:1]
	ds_write2_b32 v40, v32, v33 offset1:1
	s_cbranch_vccnz .LBB0_172
	s_ashr_i32 s6, s5, 31
	s_lshr_b32 s6, s6, 26
	s_add_i32 s6, s5, s6
	s_and_b32 s7, s6, 0xffffffc0
	s_lshl_b32 s6, s6, 5
	v_or_b32_e32 v26, s7, v1
	s_and_b32 s6, s6, 0xfffff800
	v_ashrrev_i32_e32 v27, 31, v26
	s_sub_i32 s6, s4, s6
	v_lshlrev_b64 v[2:3], 13, v[26:27]
	v_or_b32_e32 v4, 8, v26
	v_or_b32_e32 v10, 16, v26
	v_or_b32_e32 v12, 24, v26
	v_or_b32_e32 v18, 32, v26
	v_or_b32_e32 v20, 40, v26
	v_or_b32_e32 v30, 48, v26
	v_or_b32_e32 v26, 56, v26
	s_ashr_i32 s7, s6, 31
	v_ashrrev_i32_e32 v5, 31, v4
	v_ashrrev_i32_e32 v11, 31, v10
	v_ashrrev_i32_e32 v13, 31, v12
	v_ashrrev_i32_e32 v19, 31, v18
	v_ashrrev_i32_e32 v21, 31, v20
	v_ashrrev_i32_e32 v31, 31, v30
	v_ashrrev_i32_e32 v27, 31, v26
	v_lshl_add_u64 v[28:29], s[6:7], 2, v[34:35]
	v_lshlrev_b64 v[4:5], 13, v[4:5]
	v_lshlrev_b64 v[10:11], 13, v[10:11]
	v_lshlrev_b64 v[12:13], 13, v[12:13]
	v_lshlrev_b64 v[18:19], 13, v[18:19]
	v_lshlrev_b64 v[20:21], 13, v[20:21]
	v_lshlrev_b64 v[30:31], 13, v[30:31]
	v_lshlrev_b64 v[26:27], 13, v[26:27]
	v_lshl_add_u64 v[2:3], v[28:29], 0, v[2:3]
	v_lshl_add_u64 v[6:7], v[28:29], 0, v[4:5]
	v_lshl_add_u64 v[10:11], v[28:29], 0, v[10:11]
	v_lshl_add_u64 v[14:15], v[28:29], 0, v[12:13]
	v_lshl_add_u64 v[18:19], v[28:29], 0, v[18:19]
	v_lshl_add_u64 v[22:23], v[28:29], 0, v[20:21]
	v_lshl_add_u64 v[30:31], v[28:29], 0, v[30:31]
	v_lshl_add_u64 v[32:33], v[28:29], 0, v[26:27]
	global_load_dwordx4 v[2:5], v[2:3], off nt
	s_nop 0
	global_load_dwordx4 v[6:9], v[6:7], off nt
	s_nop 0
	global_load_dwordx4 v[10:13], v[10:11], off nt
	s_nop 0
	global_load_dwordx4 v[14:17], v[14:15], off nt
	s_nop 0
	global_load_dwordx4 v[18:21], v[18:19], off nt
	s_nop 0
	global_load_dwordx4 v[22:25], v[22:23], off nt
	s_nop 0
	global_load_dwordx4 v[26:29], v[30:31], off nt
	s_nop 0
	global_load_dwordx4 v[30:33], v[32:33], off nt
	s_branch .LBB0_172

.LBB0_313:
.LBB0_314:
	s_cmp_lt_i32 s72, 4
	s_cselect_b64 s[4:5], -1, 0
	s_add_u32 s6, s70, 0x3b00000
	s_addc_u32 s7, s71, 0
	s_add_u32 s44, s70, 0x12600000
	s_addc_u32 s45, s71, 0
	s_add_u32 s50, s70, 0x16a00000
	s_addc_u32 s51, s71, 0
	s_and_b64 s[8:9], s[4:5], s[0:1]
	s_andn2_b64 vcc, exec, s[8:9]
	s_cbranch_vccnz .LBB0_361
	s_add_u32 s4, s70, 0x1ae00000
	s_addc_u32 s5, s71, 0
	s_cmp_gt_i32 s2, 63
	s_mov_b64 s[0:1], -1
	s_cbranch_scc0 .LBB0_346
	s_sub_i32 s3, s2, 64
	s_waitcnt vmcnt(0)
	v_and_b32_e32 v1, 0x7f, v143
	v_lshrrev_b32_e32 v70, 7, v143
	v_mov_b32_e32 v98, 0
	s_cmpk_lt_u32 s3, 0x800
	v_readfirstlane_b32 s10, v143
	v_mov_b32_e32 v85, 0
	s_cselect_b64 s[0:1], -1, 0
	s_cmpk_gt_u32 s3, 0x7ff
	v_lshlrev_b32_e32 v2, 2, v1
	v_lshlrev_b32_e32 v68, 14, v70
	v_mov_b32_e32 v97, 0
	v_mov_b32_e32 v84, 0
	v_mov_b32_e32 v83, 0
	v_mov_b32_e32 v82, 0
	v_mov_b32_e32 v4, 0
	v_mov_b32_e32 v5, v98
	v_mov_b32_e32 v6, 0
	v_mov_b32_e32 v7, v98
	v_mov_b32_e32 v8, 0
	v_mov_b32_e32 v9, v98
	v_mov_b32_e32 v10, 0
	v_mov_b32_e32 v11, v98
	v_mov_b32_e32 v12, 0
	v_mov_b32_e32 v13, v98
	v_mov_b32_e32 v14, 0
	v_mov_b32_e32 v15, v98
	v_mov_b32_e32 v18, 0
	v_mov_b32_e32 v19, v98
	v_mov_b32_e32 v22, 0
	v_mov_b32_e32 v23, v98
	v_mov_b32_e32 v16, 0
	v_mov_b32_e32 v17, v98
	v_mov_b32_e32 v20, 0
	v_mov_b32_e32 v21, v98
	v_mov_b32_e32 v24, 0
	v_mov_b32_e32 v25, v98
	v_mov_b32_e32 v26, 0
	v_mov_b32_e32 v27, v98
	v_mov_b32_e32 v28, 0
	v_mov_b32_e32 v29, v98
	v_mov_b32_e32 v30, 0
	v_mov_b32_e32 v31, v98
	v_mov_b32_e32 v32, 0
	v_mov_b32_e32 v33, v98
	v_mov_b32_e32 v34, 0
	v_mov_b32_e32 v35, v98
	s_cbranch_scc1 .LBB0_318
	s_lshl_b32 s12, s3, 14
	s_mov_b32 s13, 0
	v_readlane_b32 s76, v242, 31
	s_lshl_b64 s[12:13], s[12:13], 2
	v_readlane_b32 s80, v242, 35
	v_readlane_b32 s81, v242, 36
	s_add_u32 s12, s80, s12
	s_addc_u32 s13, s81, s13
	v_mov_b32_e32 v3, 0
	v_lshl_add_u64 v[4:5], s[12:13], 0, v[2:3]
	v_mov_b32_e32 v69, v3
	v_lshl_add_u64 v[14:15], v[4:5], 0, v[68:69]
	s_movk_i32 s11, 0x1000
	v_add_co_u32_e32 v28, vcc, s11, v14
	s_movk_i32 s11, 0x2000
	s_nop 0
	v_addc_co_u32_e32 v29, vcc, 0, v15, vcc
	v_add_co_u32_e32 v18, vcc, s11, v14
	s_movk_i32 s11, 0x3000
	s_nop 0
	v_addc_co_u32_e32 v19, vcc, 0, v15, vcc
	v_add_co_u32_e32 v36, vcc, s11, v14
	global_load_dword v4, v[14:15], off nt
	global_load_dword v5, v[14:15], off offset:512 nt
	global_load_dword v6, v[14:15], off offset:1024 nt
	global_load_dword v7, v[14:15], off offset:1536 nt
	global_load_dword v8, v[14:15], off offset:2048 nt
	global_load_dword v9, v[14:15], off offset:2560 nt
	global_load_dword v10, v[14:15], off offset:3072 nt
	global_load_dword v11, v[14:15], off offset:3584 nt
	global_load_dword v12, v[18:19], off offset:-4096 nt
	global_load_dword v16, v[18:19], off nt
	global_load_dword v17, v[18:19], off offset:512 nt
	global_load_dword v20, v[18:19], off offset:1024 nt
	global_load_dword v21, v[18:19], off offset:1536 nt
	global_load_dword v24, v[18:19], off offset:2048 nt
	global_load_dword v25, v[18:19], off offset:2560 nt
	global_load_dword v26, v[18:19], off offset:3072 nt
	global_load_dword v27, v[18:19], off offset:3584 nt
	v_addc_co_u32_e32 v37, vcc, 0, v15, vcc
	global_load_dword v13, v[28:29], off offset:512 nt
	global_load_dword v14, v[28:29], off offset:1024 nt
	global_load_dword v15, v[28:29], off offset:1536 nt
	global_load_dword v18, v[28:29], off offset:2048 nt
	global_load_dword v19, v[28:29], off offset:2560 nt
	global_load_dword v22, v[28:29], off offset:3072 nt
	global_load_dword v23, v[28:29], off offset:3584 nt
	s_nop 0
	global_load_dword v28, v[36:37], off nt
	global_load_dword v29, v[36:37], off offset:512 nt
	global_load_dword v30, v[36:37], off offset:1024 nt
	global_load_dword v31, v[36:37], off offset:1536 nt
	global_load_dword v32, v[36:37], off offset:2048 nt
	global_load_dword v33, v[36:37], off offset:2560 nt
	global_load_dword v34, v[36:37], off offset:3072 nt
	global_load_dword v35, v[36:37], off offset:3584 nt
	s_lshl_b32 s11, s3, 7
	s_lshr_b32 s12, s3, 2
	s_and_b32 s11, s11, 0x780
	s_and_b32 s12, s12, 0x1fc
	v_add_lshl_u32 v3, s12, v70, 11
	v_or_b32_e32 v36, s11, v1
	s_mov_b32 s11, 0x1000000
	v_or3_b32 v3, v3, v36, s11
	v_readlane_b32 s12, v242, 51
	v_readlane_b32 s77, v242, 32
	v_readlane_b32 s78, v242, 33
	v_readlane_b32 s79, v242, 34
	v_readlane_b32 s82, v242, 37
	v_readlane_b32 s83, v242, 38
	v_readlane_b32 s84, v242, 39
	v_readlane_b32 s85, v242, 40
	v_readlane_b32 s86, v242, 41
	v_readlane_b32 s87, v242, 42
	v_readlane_b32 s88, v242, 43
	v_readlane_b32 s89, v242, 44
	v_readlane_b32 s90, v242, 45
	v_readlane_b32 s91, v242, 46
	v_lshlrev_b32_e32 v37, 2, v3
	v_readlane_b32 s13, v242, 52
	v_lshlrev_b32_e32 v3, 1, v3
	s_nop 3
	global_load_dword v82, v37, s[12:13] nt
	global_load_ushort v83, v3, s[38:39]
	global_load_ushort v84, v3, s[48:49]
	global_load_ushort v97, v3, s[4:5]
	v_readlane_b32 s76, v242, 12
	v_lshlrev_b32_e32 v3, 2, v36
	v_readlane_b32 s82, v242, 18
	v_readlane_b32 s83, v242, 19
	s_mov_b32 s33, s96
	v_readlane_b32 s77, v242, 13
	v_readlane_b32 s78, v242, 14
	v_readlane_b32 s79, v242, 15
	v_readlane_b32 s80, v242, 16
	global_load_dword v98, v3, s[82:83] nt
	v_readlane_b32 s81, v242, 17
	v_readlane_b32 s84, v242, 20
	v_readlane_b32 s85, v242, 21
	v_readlane_b32 s86, v242, 22
	v_readlane_b32 s87, v242, 23
	v_readlane_b32 s88, v242, 24
	v_readlane_b32 s89, v242, 25
	v_readlane_b32 s90, v242, 26
	v_readlane_b32 s91, v242, 27
.LBB0_318:
	s_sub_i32 s24, s74, 64
	s_add_i32 s11, s24, s3
	s_cmpk_gt_i32 s11, 0x7ff
	v_mov_b32_e32 v87, 0
	v_mov_b32_e32 v86, 0
	v_mov_b32_e32 v88, 0
	v_mov_b32_e32 v69, 0
	s_cbranch_scc1 .LBB0_320
	s_lshl_b32 s12, s11, 16
	v_readlane_b32 s76, v242, 31
	s_and_b32 s12, s12, 0x7ff0000
	v_readlane_b32 s80, v242, 35
	v_readlane_b32 s81, v242, 36
	s_add_u32 s12, s80, s12
	s_addc_u32 s13, s81, 0
	v_mov_b32_e32 v3, 0
	v_lshl_add_u64 v[36:37], s[12:13], 0, v[2:3]
	v_mov_b32_e32 v69, v3
	v_lshl_add_u64 v[52:53], v[36:37], 0, v[68:69]
	s_movk_i32 s12, 0x1000
	v_add_co_u32_e32 v60, vcc, s12, v52
	s_movk_i32 s12, 0x2000
	s_nop 0
	v_addc_co_u32_e32 v61, vcc, 0, v53, vcc
	v_add_co_u32_e32 v56, vcc, s12, v52
	s_movk_i32 s12, 0x3000
	s_nop 0
	v_addc_co_u32_e32 v57, vcc, 0, v53, vcc
	v_add_co_u32_e32 v68, vcc, s12, v52
	global_load_dword v36, v[52:53], off nt
	global_load_dword v37, v[52:53], off offset:512 nt
	global_load_dword v38, v[52:53], off offset:1024 nt
	global_load_dword v39, v[52:53], off offset:1536 nt
	global_load_dword v40, v[52:53], off offset:2048 nt
	global_load_dword v41, v[52:53], off offset:2560 nt
	global_load_dword v42, v[52:53], off offset:3072 nt
	global_load_dword v43, v[52:53], off offset:3584 nt
	global_load_dword v44, v[56:57], off offset:-4096 nt
	global_load_dword v46, v[56:57], off nt
	global_load_dword v47, v[56:57], off offset:512 nt
	global_load_dword v48, v[56:57], off offset:1024 nt
	global_load_dword v49, v[56:57], off offset:1536 nt
	global_load_dword v50, v[56:57], off offset:2048 nt
	global_load_dword v51, v[56:57], off offset:2560 nt
	global_load_dword v54, v[56:57], off offset:3072 nt
	global_load_dword v55, v[56:57], off offset:3584 nt
	v_addc_co_u32_e32 v69, vcc, 0, v53, vcc
	global_load_dword v45, v[60:61], off offset:512 nt
	global_load_dword v52, v[60:61], off offset:1024 nt
	global_load_dword v53, v[60:61], off offset:1536 nt
	global_load_dword v56, v[60:61], off offset:2048 nt
	global_load_dword v57, v[60:61], off offset:2560 nt
	global_load_dword v58, v[60:61], off offset:3072 nt
	global_load_dword v59, v[60:61], off offset:3584 nt
	s_nop 0
	global_load_dword v60, v[68:69], off nt
	global_load_dword v61, v[68:69], off offset:512 nt
	global_load_dword v62, v[68:69], off offset:1024 nt
	global_load_dword v63, v[68:69], off offset:1536 nt
	global_load_dword v64, v[68:69], off offset:2048 nt
	global_load_dword v65, v[68:69], off offset:2560 nt
	global_load_dword v66, v[68:69], off offset:3072 nt
	global_load_dword v67, v[68:69], off offset:3584 nt
	s_lshl_b32 s12, s11, 7
	s_lshr_b32 s11, s11, 2
	s_and_b32 s12, s12, 0x780
	s_and_b32 s11, s11, 0x1fc
	v_add_lshl_u32 v3, s11, v70, 11
	v_or_b32_e32 v68, s12, v1
	s_mov_b32 s11, 0x1000000
	v_or3_b32 v3, v3, v68, s11
	v_readlane_b32 s12, v242, 51
	v_readlane_b32 s77, v242, 32
	v_readlane_b32 s78, v242, 33
	v_readlane_b32 s79, v242, 34
	v_readlane_b32 s82, v242, 37
	v_readlane_b32 s83, v242, 38
	v_readlane_b32 s84, v242, 39
	v_readlane_b32 s85, v242, 40
	v_readlane_b32 s86, v242, 41
	v_readlane_b32 s87, v242, 42
	v_readlane_b32 s88, v242, 43
	v_readlane_b32 s89, v242, 44
	v_readlane_b32 s90, v242, 45
	v_readlane_b32 s91, v242, 46
	v_lshlrev_b32_e32 v69, 2, v3
	v_readlane_b32 s13, v242, 52
	v_lshlrev_b32_e32 v3, 1, v3
	s_nop 3
	global_load_dword v69, v69, s[12:13] nt
	s_nop 0
	global_load_ushort v86, v3, s[38:39]
	global_load_ushort v87, v3, s[48:49]
	global_load_ushort v85, v3, s[4:5]
	v_readlane_b32 s76, v242, 12
	v_lshlrev_b32_e32 v3, 2, v68
	v_readlane_b32 s82, v242, 18
	v_readlane_b32 s83, v242, 19
	s_mov_b32 s33, s96
	v_readlane_b32 s77, v242, 13
	v_readlane_b32 s78, v242, 14
	v_readlane_b32 s79, v242, 15
	v_readlane_b32 s80, v242, 16
	global_load_dword v88, v3, s[82:83] nt
	v_readlane_b32 s81, v242, 17
	v_readlane_b32 s84, v242, 20
	v_readlane_b32 s85, v242, 21
	v_readlane_b32 s86, v242, 22
	v_readlane_b32 s87, v242, 23
	v_readlane_b32 s88, v242, 24
	v_readlane_b32 s89, v242, 25
	v_readlane_b32 s90, v242, 26
	v_readlane_b32 s91, v242, 27

.LBB0_325:
	v_add_u32_e32 v77, s10, v92
	v_add_u32_e32 v79, s10, v93
	ds_read_b32 v200, v77
	ds_read_b128 v[100:103], v79
	ds_read_b128 v[104:107], v79 offset:16
	ds_read_b128 v[108:111], v79 offset:32
	ds_read_b128 v[112:115], v79 offset:2064
	ds_read_b128 v[116:119], v79 offset:2080
	ds_read_b128 v[120:123], v79 offset:4112
	ds_read_b128 v[124:127], v79 offset:4128
	ds_read_b128 v[128:131], v79 offset:48
	ds_read_b128 v[132:135], v79 offset:64
	ds_read_b128 v[136:139], v79 offset:2096
	ds_read_b128 v[144:147], v79 offset:2112
	ds_read_b128 v[148:151], v79 offset:4144
	ds_read_b128 v[152:155], v79 offset:4160
	ds_read_b128 v[156:159], v79 offset:80
	ds_read_b128 v[160:163], v79 offset:96
	ds_read_b128 v[164:167], v79 offset:2128
	ds_read_b128 v[168:171], v79 offset:2144
	ds_read_b128 v[172:175], v79 offset:4176
	ds_read_b128 v[176:179], v79 offset:4192
	ds_read_b128 v[180:183], v79 offset:2048
	ds_read_b128 v[184:187], v79 offset:112
	ds_read_b128 v[188:191], v79 offset:4096
	ds_read_b128 v[192:195], v79 offset:2160
	ds_read_b128 v[196:199], v79 offset:4208
	s_waitcnt lgkmcnt(4)
	v_pk_mul_f32 v[180:181], v[200:201], v[180:181] op_sel_hi:[0,1]
	v_pk_fma_f32 v[4:5], v[4:5], v[100:101], v[180:181]
	v_pk_mul_f32 v[182:183], v[200:201], v[182:183] op_sel_hi:[0,1]
	s_waitcnt lgkmcnt(2)
	v_fma_f32 v77, v188, v4, 0
	v_pk_fma_f32 v[6:7], v[6:7], v[102:103], v[182:183]
	v_fmac_f32_e32 v77, v189, v5
	v_pk_mul_f32 v[112:113], v[200:201], v[112:113] op_sel_hi:[0,1]
	v_fmac_f32_e32 v77, v190, v6
	v_pk_fma_f32 v[8:9], v[8:9], v[104:105], v[112:113]
	v_fmac_f32_e32 v77, v191, v7
	v_pk_mul_f32 v[114:115], v[200:201], v[114:115] op_sel_hi:[0,1]
	v_fmac_f32_e32 v77, v120, v8
	v_pk_fma_f32 v[10:11], v[10:11], v[106:107], v[114:115]
	v_fmac_f32_e32 v77, v121, v9
	v_pk_mul_f32 v[116:117], v[200:201], v[116:117] op_sel_hi:[0,1]
	v_fmac_f32_e32 v77, v122, v10
	v_pk_fma_f32 v[12:13], v[12:13], v[108:109], v[116:117]
	v_fmac_f32_e32 v77, v123, v11
	v_pk_mul_f32 v[118:119], v[200:201], v[118:119] op_sel_hi:[0,1]
	v_fmac_f32_e32 v77, v124, v12
	v_pk_fma_f32 v[14:15], v[14:15], v[110:111], v[118:119]
	v_fmac_f32_e32 v77, v125, v13
	v_pk_mul_f32 v[136:137], v[200:201], v[136:137] op_sel_hi:[0,1]
	v_fmac_f32_e32 v77, v126, v14
	v_pk_fma_f32 v[18:19], v[18:19], v[128:129], v[136:137]
	v_fmac_f32_e32 v77, v127, v15
	v_pk_mul_f32 v[138:139], v[200:201], v[138:139] op_sel_hi:[0,1]
	v_fmac_f32_e32 v77, v148, v18
	v_pk_fma_f32 v[22:23], v[22:23], v[130:131], v[138:139]
	v_fmac_f32_e32 v77, v149, v19
	v_pk_mul_f32 v[144:145], v[200:201], v[144:145] op_sel_hi:[0,1]
	v_fmac_f32_e32 v77, v150, v22
	v_pk_fma_f32 v[16:17], v[16:17], v[132:133], v[144:145]
	v_fmac_f32_e32 v77, v151, v23
	v_pk_mul_f32 v[146:147], v[200:201], v[146:147] op_sel_hi:[0,1]
	v_fmac_f32_e32 v77, v152, v16
	v_pk_mul_f32 v[164:165], v[200:201], v[164:165] op_sel_hi:[0,1]
	v_pk_fma_f32 v[20:21], v[20:21], v[134:135], v[146:147]
	v_fmac_f32_e32 v77, v153, v17
	v_pk_fma_f32 v[24:25], v[24:25], v[156:157], v[164:165]
	v_fmac_f32_e32 v77, v154, v20
	v_pk_mul_f32 v[166:167], v[200:201], v[166:167] op_sel_hi:[0,1]
	v_pk_mul_f32 v[102:103], v[172:173], v[24:25]
	v_fmac_f32_e32 v77, v155, v21
	v_pk_fma_f32 v[26:27], v[26:27], v[158:159], v[166:167]
	v_add_f32_e32 v77, v102, v77
	v_pk_mul_f32 v[168:169], v[200:201], v[168:169] op_sel_hi:[0,1]
	v_pk_mul_f32 v[104:105], v[174:175], v[26:27]
	v_add_f32_e32 v77, v103, v77
	v_pk_fma_f32 v[28:29], v[28:29], v[160:161], v[168:169]
	v_add_f32_e32 v77, v104, v77
	v_pk_mul_f32 v[170:171], v[200:201], v[170:171] op_sel_hi:[0,1]
	v_pk_mul_f32 v[106:107], v[176:177], v[28:29]
	v_add_f32_e32 v77, v105, v77
	v_pk_fma_f32 v[30:31], v[30:31], v[162:163], v[170:171]
	v_add_f32_e32 v77, v106, v77
	v_mov_b32_e32 v140, v35
	s_waitcnt lgkmcnt(1)
	v_pk_mul_f32 v[192:193], v[200:201], v[192:193] op_sel_hi:[0,1]
	v_mul_f32_e32 v34, v34, v186
	v_mul_f32_e32 v186, v200, v194
	v_mov_b32_e32 v141, v200
	v_mov_b32_e32 v194, v187
	v_pk_mul_f32 v[108:109], v[178:179], v[30:31]
	v_add_f32_e32 v77, v107, v77
	v_pk_fma_f32 v[32:33], v[32:33], v[184:185], v[192:193]
	v_pk_mul_f32 v[100:101], v[140:141], v[194:195]
	v_add_f32_e32 v77, v108, v77
	s_waitcnt lgkmcnt(0)
	v_pk_mul_f32 v[110:111], v[196:197], v[32:33]
	v_mov_b32_e32 v35, v100
	v_mov_b32_e32 v187, v101
	v_add_f32_e32 v77, v109, v77
	v_pk_add_f32 v[34:35], v[34:35], v[186:187]
	v_add_f32_e32 v77, v110, v77
	v_pk_mul_f32 v[100:101], v[198:199], v[34:35]
	v_add_f32_e32 v77, v111, v77
	v_add_f32_e32 v77, v100, v77
	s_addk_i32 s10, 0x200
	v_add_f32_e32 v77, v101, v77
	s_cmpk_eq_i32 s10, 0x800
	ds_write_b32 v70, v77
	v_add_u32_e32 v70, 0x800, v70
	s_cbranch_scc0 .LBB0_325
	s_lshl_b32 s10, s29, 16
	s_and_b32 s10, s10, 0x7ff0000
	v_lshl_add_u64 v[100:101], v[72:73], 0, s[10:11]
	v_lshlrev_b32_e32 v70, 2, v68
	v_lshl_add_u64 v[102:103], v[100:101], 0, v[70:71]
	v_mov_b32_e32 v77, v71
	global_store_dword v[102:103], v4, off nt
	global_store_dword v[102:103], v5, off offset:512 nt
	global_store_dword v[102:103], v6, off offset:1024 nt
	global_store_dword v[102:103], v7, off offset:1536 nt
	global_store_dword v[102:103], v8, off offset:2048 nt
	global_store_dword v[102:103], v9, off offset:2560 nt
	global_store_dword v[102:103], v10, off offset:3072 nt
	global_store_dword v[102:103], v11, off offset:3584 nt
	v_lshl_add_u64 v[102:103], v[100:101], 0, v[76:77]
	v_mov_b32_e32 v79, v71
	v_mov_b32_e32 v81, v71
	s_add_i32 s28, s29, s25
	global_store_dword v[102:103], v12, off nt
	global_store_dword v[102:103], v13, off offset:512 nt
	global_store_dword v[102:103], v14, off offset:1024 nt
	global_store_dword v[102:103], v15, off offset:1536 nt
	global_store_dword v[102:103], v18, off offset:2048 nt
	global_store_dword v[102:103], v19, off offset:2560 nt
	global_store_dword v[102:103], v22, off offset:3072 nt
	global_store_dword v[102:103], v23, off offset:3584 nt
	v_lshl_add_u64 v[102:103], v[100:101], 0, v[78:79]
	v_lshl_add_u64 v[100:101], v[100:101], 0, v[80:81]
	s_cmpk_gt_i32 s28, 0x7ff
	global_store_dword v[102:103], v16, off nt
	global_store_dword v[102:103], v17, off offset:512 nt
	global_store_dword v[102:103], v20, off offset:1024 nt
	global_store_dword v[102:103], v21, off offset:1536 nt
	global_store_dword v[102:103], v24, off offset:2048 nt
	global_store_dword v[102:103], v25, off offset:2560 nt
	global_store_dword v[102:103], v26, off offset:3072 nt
	global_store_dword v[102:103], v27, off offset:3584 nt
	global_store_dword v[100:101], v28, off nt
	global_store_dword v[100:101], v29, off offset:512 nt
	global_store_dword v[100:101], v30, off offset:1024 nt
	global_store_dword v[100:101], v31, off offset:1536 nt
	global_store_dword v[100:101], v32, off offset:2048 nt
	global_store_dword v[100:101], v33, off offset:2560 nt
	global_store_dword v[100:101], v34, off offset:3072 nt
	global_store_dword v[100:101], v35, off offset:3584 nt
	s_cselect_b64 s[12:13], -1, 0
	s_cmpk_lt_i32 s28, 0x800
	s_waitcnt vmcnt(33)
	v_mov_b32_e32 v99, v97
	s_waitcnt vmcnt(32)
	v_mov_b32_e32 v100, v98
	s_cbranch_scc0 .LBB0_328
	s_lshl_b32 s10, s28, 16
	s_and_b32 s10, s10, 0x7ff0000
	v_lshl_add_u64 v[28:29], v[74:75], 0, s[10:11]
	v_lshl_add_u64 v[12:13], v[28:29], 0, v[70:71]
	v_lshl_add_u64 v[16:17], v[28:29], 0, v[76:77]
	v_lshl_add_u64 v[30:31], v[28:29], 0, v[78:79]
	v_lshl_add_u64 v[82:83], v[28:29], 0, v[80:81]
	s_lshl_b32 s10, s28, 7
	s_lshr_b32 s22, s28, 2
	global_load_dword v4, v[12:13], off nt
	global_load_dword v5, v[12:13], off offset:512 nt
	global_load_dword v6, v[12:13], off offset:1024 nt
	global_load_dword v7, v[12:13], off offset:1536 nt
	global_load_dword v8, v[12:13], off offset:2048 nt
	global_load_dword v9, v[12:13], off offset:2560 nt
	global_load_dword v10, v[12:13], off offset:3072 nt
	global_load_dword v11, v[12:13], off offset:3584 nt
	s_nop 0
	global_load_dword v12, v[16:17], off nt
	global_load_dword v13, v[16:17], off offset:512 nt
	global_load_dword v14, v[16:17], off offset:1024 nt
	global_load_dword v15, v[16:17], off offset:1536 nt
	global_load_dword v18, v[16:17], off offset:2048 nt
	global_load_dword v19, v[16:17], off offset:2560 nt
	global_load_dword v22, v[16:17], off offset:3072 nt
	global_load_dword v23, v[16:17], off offset:3584 nt
	s_nop 0
	global_load_dword v16, v[30:31], off nt
	global_load_dword v17, v[30:31], off offset:512 nt
	global_load_dword v20, v[30:31], off offset:1024 nt
	global_load_dword v21, v[30:31], off offset:1536 nt
	global_load_dword v24, v[30:31], off offset:2048 nt
	global_load_dword v25, v[30:31], off offset:2560 nt
	global_load_dword v26, v[30:31], off offset:3072 nt
	global_load_dword v27, v[30:31], off offset:3584 nt
	global_load_dword v28, v[82:83], off nt
	global_load_dword v29, v[82:83], off offset:512 nt
	s_nop 0
	global_load_dword v30, v[82:83], off offset:1024 nt
	global_load_dword v31, v[82:83], off offset:1536 nt
	global_load_dword v32, v[82:83], off offset:2048 nt
	global_load_dword v33, v[82:83], off offset:2560 nt
	global_load_dword v34, v[82:83], off offset:3072 nt
	global_load_dword v35, v[82:83], off offset:3584 nt
	s_and_b32 s10, s10, 0x780
	s_and_b32 s22, s22, 0x1fc
	v_add_u32_e32 v77, s22, v89
	v_or_b32_e32 v79, s10, v1
	v_lshl_or_b32 v77, v77, 11, v79
	v_readlane_b32 s22, v242, 51
	v_lshlrev_b32_e32 v81, 2, v77
	v_readlane_b32 s23, v242, 52
	v_lshlrev_b32_e32 v77, 1, v77
	s_nop 3
	global_load_dword v82, v81, s[22:23] nt
	global_load_ushort v83, v77, s[38:39]
	global_load_ushort v84, v77, s[48:49]
	global_load_ushort v99, v77, s[4:5]
	v_readlane_b32 s76, v242, 12
	v_lshlrev_b32_e32 v77, 2, v79
	v_readlane_b32 s82, v242, 18
	v_readlane_b32 s83, v242, 19
	s_mov_b32 s33, s96
	v_readlane_b32 s77, v242, 13
	v_readlane_b32 s78, v242, 14
	v_readlane_b32 s79, v242, 15
	v_readlane_b32 s80, v242, 16
	global_load_dword v100, v77, s[82:83] nt
	v_readlane_b32 s81, v242, 17
	v_readlane_b32 s84, v242, 20
	v_readlane_b32 s85, v242, 21
	v_readlane_b32 s86, v242, 22
	v_readlane_b32 s87, v242, 23
	v_readlane_b32 s88, v242, 24
	v_readlane_b32 s89, v242, 25
	v_readlane_b32 s90, v242, 26
	v_readlane_b32 s91, v242, 27

.LBB0_332:
	v_add_u32_e32 v79, s10, v92
	v_add_u32_e32 v81, s10, v93
	ds_read_b32 v98, v79
	ds_read_b128 v[108:111], v81
	ds_read_b128 v[112:115], v81 offset:16
	ds_read_b128 v[116:119], v81 offset:32
	ds_read_b128 v[120:123], v81 offset:2064
	ds_read_b128 v[124:127], v81 offset:2080
	ds_read_b128 v[128:131], v81 offset:4112
	ds_read_b128 v[132:135], v81 offset:4128
	ds_read_b128 v[136:139], v81 offset:48
	ds_read_b128 v[144:147], v81 offset:64
	ds_read_b128 v[148:151], v81 offset:2096
	ds_read_b128 v[152:155], v81 offset:2112
	ds_read_b128 v[156:159], v81 offset:4144
	ds_read_b128 v[160:163], v81 offset:4160
	ds_read_b128 v[164:167], v81 offset:80
	ds_read_b128 v[168:171], v81 offset:96
	ds_read_b128 v[172:175], v81 offset:2128
	ds_read_b128 v[176:179], v81 offset:2144
	ds_read_b128 v[180:183], v81 offset:4176
	ds_read_b128 v[184:187], v81 offset:4192
	ds_read_b128 v[188:191], v81 offset:2048
	ds_read_b128 v[192:195], v81 offset:112
	ds_read_b128 v[196:199], v81 offset:4096
	ds_read_b128 v[200:203], v81 offset:2160
	ds_read_b128 v[204:207], v81 offset:4208
	s_waitcnt vmcnt(2) lgkmcnt(4)
	v_pk_mul_f32 v[140:141], v[98:99], v[188:189] op_sel_hi:[0,1]
	v_pk_fma_f32 v[36:37], v[36:37], v[108:109], v[140:141]
	v_pk_mul_f32 v[188:189], v[98:99], v[190:191] op_sel_hi:[0,1]
	s_waitcnt lgkmcnt(2)
	v_fma_f32 v79, v196, v36, 0
	v_pk_fma_f32 v[38:39], v[38:39], v[110:111], v[188:189]
	v_fmac_f32_e32 v79, v197, v37
	v_pk_mul_f32 v[120:121], v[98:99], v[120:121] op_sel_hi:[0,1]
	v_fmac_f32_e32 v79, v198, v38
	v_pk_fma_f32 v[40:41], v[40:41], v[112:113], v[120:121]
	v_fmac_f32_e32 v79, v199, v39
	v_pk_mul_f32 v[122:123], v[98:99], v[122:123] op_sel_hi:[0,1]
	v_fmac_f32_e32 v79, v128, v40
	v_pk_fma_f32 v[42:43], v[42:43], v[114:115], v[122:123]
	v_fmac_f32_e32 v79, v129, v41
	v_pk_mul_f32 v[124:125], v[98:99], v[124:125] op_sel_hi:[0,1]
	v_fmac_f32_e32 v79, v130, v42
	v_pk_fma_f32 v[44:45], v[44:45], v[116:117], v[124:125]
	v_fmac_f32_e32 v79, v131, v43
	v_pk_mul_f32 v[126:127], v[98:99], v[126:127] op_sel_hi:[0,1]
	v_fmac_f32_e32 v79, v132, v44
	v_pk_fma_f32 v[52:53], v[52:53], v[118:119], v[126:127]
	v_fmac_f32_e32 v79, v133, v45
	v_pk_mul_f32 v[148:149], v[98:99], v[148:149] op_sel_hi:[0,1]
	v_fmac_f32_e32 v79, v134, v52
	v_pk_fma_f32 v[56:57], v[56:57], v[136:137], v[148:149]
	v_fmac_f32_e32 v79, v135, v53
	v_pk_mul_f32 v[150:151], v[98:99], v[150:151] op_sel_hi:[0,1]
	v_fmac_f32_e32 v79, v156, v56
	v_pk_fma_f32 v[58:59], v[58:59], v[138:139], v[150:151]
	v_fmac_f32_e32 v79, v157, v57
	v_pk_mul_f32 v[152:153], v[98:99], v[152:153] op_sel_hi:[0,1]
	v_fmac_f32_e32 v79, v158, v58
	v_pk_fma_f32 v[46:47], v[46:47], v[144:145], v[152:153]
	v_fmac_f32_e32 v79, v159, v59
	v_pk_mul_f32 v[154:155], v[98:99], v[154:155] op_sel_hi:[0,1]
	v_fmac_f32_e32 v79, v160, v46
	v_pk_mul_f32 v[172:173], v[98:99], v[172:173] op_sel_hi:[0,1]
	v_pk_fma_f32 v[48:49], v[48:49], v[146:147], v[154:155]
	v_fmac_f32_e32 v79, v161, v47
	v_pk_fma_f32 v[50:51], v[50:51], v[164:165], v[172:173]
	v_fmac_f32_e32 v79, v162, v48
	v_pk_mul_f32 v[174:175], v[98:99], v[174:175] op_sel_hi:[0,1]
	v_pk_mul_f32 v[108:109], v[180:181], v[50:51]
	v_fmac_f32_e32 v79, v163, v49
	v_pk_fma_f32 v[54:55], v[54:55], v[166:167], v[174:175]
	v_add_f32_e32 v79, v108, v79
	v_pk_mul_f32 v[176:177], v[98:99], v[176:177] op_sel_hi:[0,1]
	v_pk_mul_f32 v[110:111], v[182:183], v[54:55]
	v_add_f32_e32 v79, v109, v79
	v_pk_fma_f32 v[60:61], v[60:61], v[168:169], v[176:177]
	v_add_f32_e32 v79, v110, v79
	v_pk_mul_f32 v[178:179], v[98:99], v[178:179] op_sel_hi:[0,1]
	v_pk_mul_f32 v[112:113], v[184:185], v[60:61]
	v_add_f32_e32 v79, v111, v79
	v_pk_fma_f32 v[62:63], v[62:63], v[170:171], v[178:179]
	v_add_f32_e32 v79, v112, v79
	s_waitcnt lgkmcnt(1)
	v_pk_mul_f32 v[190:191], v[98:99], v[200:201] op_sel_hi:[0,1]
	v_pk_mul_f32 v[114:115], v[186:187], v[62:63]
	v_add_f32_e32 v79, v113, v79
	v_pk_fma_f32 v[64:65], v[64:65], v[192:193], v[190:191]
	v_add_f32_e32 v79, v114, v79
	v_pk_mul_f32 v[200:201], v[98:99], v[202:203] op_sel_hi:[0,1]
	s_waitcnt lgkmcnt(0)
	v_pk_mul_f32 v[116:117], v[204:205], v[64:65]
	v_add_f32_e32 v79, v115, v79
	v_pk_fma_f32 v[66:67], v[66:67], v[194:195], v[200:201]
	v_add_f32_e32 v79, v116, v79
	v_pk_mul_f32 v[118:119], v[206:207], v[66:67]
	v_add_f32_e32 v79, v117, v79
	v_add_f32_e32 v79, v118, v79
	s_addk_i32 s10, 0x200
	v_add_f32_e32 v79, v119, v79
	s_cmpk_eq_i32 s10, 0x800
	ds_write_b32 v77, v79
	v_add_u32_e32 v77, 0x800, v77
	s_cbranch_scc0 .LBB0_332
	s_lshl_b32 s10, s29, 16
	s_and_b32 s10, s10, 0x7ff0000
	v_lshl_add_u64 v[108:109], v[72:73], 0, s[10:11]
	v_lshl_add_u64 v[110:111], v[108:109], 0, v[70:71]
	v_mov_b32_e32 v77, v71
	global_store_dword v[110:111], v36, off nt
	global_store_dword v[110:111], v37, off offset:512 nt
	global_store_dword v[110:111], v38, off offset:1024 nt
	global_store_dword v[110:111], v39, off offset:1536 nt
	global_store_dword v[110:111], v40, off offset:2048 nt
	global_store_dword v[110:111], v41, off offset:2560 nt
	global_store_dword v[110:111], v42, off offset:3072 nt
	global_store_dword v[110:111], v43, off offset:3584 nt
	v_lshl_add_u64 v[110:111], v[108:109], 0, v[76:77]
	v_mov_b32_e32 v79, v71
	v_mov_b32_e32 v81, v71
	global_store_dword v[110:111], v44, off nt
	global_store_dword v[110:111], v45, off offset:512 nt
	global_store_dword v[110:111], v52, off offset:1024 nt
	global_store_dword v[110:111], v53, off offset:1536 nt
	global_store_dword v[110:111], v56, off offset:2048 nt
	global_store_dword v[110:111], v57, off offset:2560 nt
	global_store_dword v[110:111], v58, off offset:3072 nt
	global_store_dword v[110:111], v59, off offset:3584 nt
	v_lshl_add_u64 v[110:111], v[108:109], 0, v[78:79]
	v_lshl_add_u64 v[108:109], v[108:109], 0, v[80:81]
	s_add_i32 s22, s29, s25
	global_store_dword v[110:111], v46, off nt
	global_store_dword v[110:111], v47, off offset:512 nt
	global_store_dword v[110:111], v48, off offset:1024 nt
	global_store_dword v[110:111], v49, off offset:1536 nt
	global_store_dword v[110:111], v50, off offset:2048 nt
	global_store_dword v[110:111], v51, off offset:2560 nt
	global_store_dword v[110:111], v54, off offset:3072 nt
	global_store_dword v[110:111], v55, off offset:3584 nt
	global_store_dword v[108:109], v60, off nt
	global_store_dword v[108:109], v61, off offset:512 nt
	global_store_dword v[108:109], v62, off offset:1024 nt
	global_store_dword v[108:109], v63, off offset:1536 nt
	global_store_dword v[108:109], v64, off offset:2048 nt
	global_store_dword v[108:109], v65, off offset:2560 nt
	global_store_dword v[108:109], v66, off offset:3072 nt
	global_store_dword v[108:109], v67, off offset:3584 nt
	s_cmpk_lt_i32 s22, 0x800
	v_mov_b32_e32 v108, v85
	v_mov_b32_e32 v97, v88
	s_cbranch_scc0 .LBB0_335
	s_lshl_b32 s10, s22, 16
	s_and_b32 s10, s10, 0x7ff0000
	v_lshl_add_u64 v[60:61], v[74:75], 0, s[10:11]
	v_lshl_add_u64 v[44:45], v[60:61], 0, v[70:71]
	v_lshl_add_u64 v[46:47], v[60:61], 0, v[76:77]
	v_lshl_add_u64 v[62:63], v[60:61], 0, v[78:79]
	v_lshl_add_u64 v[86:87], v[60:61], 0, v[80:81]
	s_lshl_b32 s10, s22, 7
	s_lshr_b32 s22, s22, 2
	global_load_dword v36, v[44:45], off nt
	global_load_dword v37, v[44:45], off offset:512 nt
	global_load_dword v38, v[44:45], off offset:1024 nt
	global_load_dword v39, v[44:45], off offset:1536 nt
	global_load_dword v40, v[44:45], off offset:2048 nt
	global_load_dword v41, v[44:45], off offset:2560 nt
	global_load_dword v42, v[44:45], off offset:3072 nt
	global_load_dword v43, v[44:45], off offset:3584 nt
	s_nop 0
	global_load_dword v44, v[46:47], off nt
	global_load_dword v45, v[46:47], off offset:512 nt
	global_load_dword v52, v[46:47], off offset:1024 nt
	global_load_dword v53, v[46:47], off offset:1536 nt
	global_load_dword v56, v[46:47], off offset:2048 nt
	global_load_dword v57, v[46:47], off offset:2560 nt
	global_load_dword v58, v[46:47], off offset:3072 nt
	global_load_dword v59, v[46:47], off offset:3584 nt
	s_nop 0
	global_load_dword v46, v[62:63], off nt
	global_load_dword v47, v[62:63], off offset:512 nt
	global_load_dword v48, v[62:63], off offset:1024 nt
	global_load_dword v49, v[62:63], off offset:1536 nt
	global_load_dword v50, v[62:63], off offset:2048 nt
	global_load_dword v51, v[62:63], off offset:2560 nt
	global_load_dword v54, v[62:63], off offset:3072 nt
	global_load_dword v55, v[62:63], off offset:3584 nt
	global_load_dword v60, v[86:87], off nt
	global_load_dword v61, v[86:87], off offset:512 nt
	s_nop 0
	global_load_dword v62, v[86:87], off offset:1024 nt
	global_load_dword v63, v[86:87], off offset:1536 nt
	global_load_dword v64, v[86:87], off offset:2048 nt
	global_load_dword v65, v[86:87], off offset:2560 nt
	global_load_dword v66, v[86:87], off offset:3072 nt
	global_load_dword v67, v[86:87], off offset:3584 nt
	s_and_b32 s10, s10, 0x780
	s_and_b32 s22, s22, 0x1fc
	v_add_u32_e32 v69, s22, v89
	v_or_b32_e32 v70, s10, v1
	v_lshl_or_b32 v69, v69, 11, v70
	v_readlane_b32 s22, v242, 51
	v_lshlrev_b32_e32 v77, 2, v69
	v_readlane_b32 s23, v242, 52
	v_lshlrev_b32_e32 v79, 1, v69
	s_nop 3
	global_load_dword v69, v77, s[22:23] nt
	global_load_ushort v86, v79, s[38:39]
	global_load_ushort v87, v79, s[48:49]
	global_load_ushort v108, v79, s[4:5]
	v_readlane_b32 s76, v242, 12
	v_lshlrev_b32_e32 v70, 2, v70
	v_readlane_b32 s82, v242, 18
	v_readlane_b32 s83, v242, 19
	s_mov_b32 s33, s96
	v_readlane_b32 s77, v242, 13
	v_readlane_b32 s78, v242, 14
	v_readlane_b32 s79, v242, 15
	v_readlane_b32 s80, v242, 16
	global_load_dword v97, v70, s[82:83] nt
	v_readlane_b32 s81, v242, 17
	v_readlane_b32 s84, v242, 20
	v_readlane_b32 s85, v242, 21
	v_readlane_b32 s86, v242, 22
	v_readlane_b32 s87, v242, 23
	v_readlane_b32 s88, v242, 24
	v_readlane_b32 s89, v242, 25
	v_readlane_b32 s90, v242, 26
	v_readlane_b32 s91, v242, 27

.LBB0_338:
	s_lshl_b32 s0, s3, 3
	v_readlane_b32 s1, v242, 28
	s_add_i32 s22, s1, s0
	s_cmpk_gt_i32 s22, 0x2bff
	s_waitcnt vmcnt(63) expcnt(7) lgkmcnt(15)
	s_barrier
	s_cbranch_scc1 .LBB0_345
	s_mul_hi_u32 s0, s22, 0xba2e8ba3
	s_lshr_b32 s10, s0, 8
	s_mul_i32 s0, s10, 0x160
	s_sub_i32 s0, s22, s0
	s_lshl_b32 s0, s0, 5
	s_mov_b32 s1, 0
	s_mov_b64 s[26:27], s[16:17]
	v_readlane_b32 s12, v242, 0
	s_lshl_b32 s3, s24, 3
	s_lshl_b64 s[0:1], s[0:1], 2
	v_readlane_b32 s16, v242, 4
	v_readlane_b32 s17, v242, 5
	s_add_u32 s0, s16, s0
	s_waitcnt vmcnt(34)
	v_and_b32_e32 v38, 7, v143
	v_lshrrev_b32_e32 v1, 3, v142
	s_addc_u32 s1, s17, s1
	v_lshlrev_b32_e32 v36, 4, v38
	v_mov_b32_e32 v37, 0
	s_waitcnt vmcnt(20)
	v_lshl_add_u64 v[26:27], s[0:1], 0, v[36:37]
	s_waitcnt vmcnt(10)
	v_lshl_or_b32 v30, s10, 6, v1
	s_mov_b32 s12, 0xb000
	v_mad_u64_u32 v[2:3], s[0:1], v30, s12, v[26:27]
	v_or_b32_e32 v4, 8, v30
	v_or_b32_e32 v10, 16, v30
	v_or_b32_e32 v12, 24, v30
	v_or_b32_e32 v18, 32, v30
	v_or_b32_e32 v20, 40, v30
	v_or_b32_e32 v28, 48, v30
	v_or_b32_e32 v30, 56, v30
	v_mad_u64_u32 v[6:7], s[0:1], v4, s12, v[26:27]
	v_mad_u64_u32 v[10:11], s[0:1], v10, s12, v[26:27]
	v_mad_u64_u32 v[14:15], s[0:1], v12, s12, v[26:27]
	v_mad_u64_u32 v[18:19], s[0:1], v18, s12, v[26:27]
	v_mad_u64_u32 v[22:23], s[0:1], v20, s12, v[26:27]
	v_mad_u64_u32 v[28:29], s[0:1], v28, s12, v[26:27]
	s_waitcnt vmcnt(9)
	v_mad_u64_u32 v[30:31], s[0:1], v30, s12, v[26:27]
	global_load_dwordx4 v[2:5], v[2:3], off nt
	s_nop 0
	global_load_dwordx4 v[6:9], v[6:7], off nt
	s_nop 0
	global_load_dwordx4 v[10:13], v[10:11], off nt
	s_nop 0
	global_load_dwordx4 v[14:17], v[14:15], off nt
	s_nop 0
	global_load_dwordx4 v[18:21], v[18:19], off nt
	s_nop 0
	global_load_dwordx4 v[22:25], v[22:23], off nt
	s_nop 0
	global_load_dwordx4 v[26:29], v[28:29], off nt
	s_nop 0
	global_load_dwordx4 v[30:33], v[30:31], off nt
	v_readlane_b32 s0, v242, 29
	v_readlane_b32 s13, v242, 1
	v_mul_u32_u24_e32 v38, 0x420, v38
	v_add_u32_e32 v42, s0, v36
	v_lshlrev_b32_e32 v39, 2, v1
	v_mul_u32_u24_e32 v43, 0x84, v1
	s_waitcnt vmcnt(13)
	v_lshl_add_u64 v[34:35], s[16:17], 0, v[36:37]
	s_mov_b64 s[16:17], s[26:27]
	v_lshl_add_u64 v[36:37], s[6:7], 0, v[36:37]
	v_add3_u32 v38, s0, v38, v39
	v_or_b32_e32 v39, 8, v1
	v_or_b32_e32 v40, 16, v1
	v_or_b32_e32 v41, 24, v1
	s_lshl_b32 s23, s22, 5
	s_lshl_b32 s13, s24, 8
	v_add_u32_e32 v42, v42, v43
	v_readlane_b32 s14, v242, 2
	v_readlane_b32 s15, v242, 3
	v_readlane_b32 s18, v242, 6
	v_readlane_b32 s19, v242, 7
	s_branch .LBB0_341

.LBB0_343:
	s_andn2_b64 vcc, exec, s[10:11]
	s_cbranch_vccnz .LBB0_340
	s_mul_hi_i32 s10, s24, 0x2e8ba2e9
	s_lshr_b32 s11, s10, 31
	s_ashr_i32 s10, s10, 6
	s_add_i32 s11, s10, s11
	s_mul_i32 s10, s11, 0xffffd400
	s_add_i32 s25, s13, s23
	s_add_i32 s10, s25, s10
	v_lshl_or_b32 v30, s11, 6, v1
	s_ashr_i32 s11, s10, 31
	v_lshl_add_u64 v[26:27], s[10:11], 2, v[34:35]
	v_mad_i64_i32 v[2:3], s[10:11], v30, s12, v[26:27]
	v_or_b32_e32 v4, 8, v30
	v_or_b32_e32 v10, 16, v30
	v_or_b32_e32 v12, 24, v30
	v_or_b32_e32 v18, 32, v30
	v_or_b32_e32 v20, 40, v30
	v_or_b32_e32 v28, 48, v30
	v_or_b32_e32 v30, 56, v30
	v_mad_i64_i32 v[6:7], s[10:11], v4, s12, v[26:27]
	v_mad_i64_i32 v[10:11], s[10:11], v10, s12, v[26:27]
	v_mad_i64_i32 v[14:15], s[10:11], v12, s12, v[26:27]
	v_mad_i64_i32 v[18:19], s[10:11], v18, s12, v[26:27]
	v_mad_i64_i32 v[22:23], s[10:11], v20, s12, v[26:27]
	v_mad_i64_i32 v[28:29], s[10:11], v28, s12, v[26:27]
	v_mad_i64_i32 v[30:31], s[10:11], v30, s12, v[26:27]
	global_load_dwordx4 v[2:5], v[2:3], off nt
	s_nop 0
	global_load_dwordx4 v[6:9], v[6:7], off nt
	s_nop 0
	global_load_dwordx4 v[10:13], v[10:11], off nt
	s_nop 0
	global_load_dwordx4 v[14:17], v[14:15], off nt
	s_nop 0
	global_load_dwordx4 v[18:21], v[18:19], off nt
	s_nop 0
	global_load_dwordx4 v[22:25], v[22:23], off nt
	s_nop 0
	global_load_dwordx4 v[26:29], v[28:29], off nt
	s_nop 0
	global_load_dwordx4 v[30:33], v[30:31], off nt
	s_branch .LBB0_340

.LBB0_1602:
	s_cmp_lt_i32 s72, 16
	s_cselect_b64 s[2:3], -1, 0
	s_and_b64 s[0:1], s[2:3], s[0:1]
	s_andn2_b64 vcc, exec, s[0:1]
	s_cbranch_vccnz .LBB0_1608
	s_cmpk_gt_i32 s96, 0x21ff
	s_cbranch_scc1 .LBB0_1608
	v_readlane_b32 s0, v242, 12
	v_readlane_b32 s1, v242, 13
	v_readlane_b32 s6, v242, 51
	v_readlane_b32 s7, v242, 52
	v_lshlrev_b32_e32 v252, 3, v142
	v_lshlrev_b32_e32 v253, 4, v142
	v_add_u32_e32 v254, 0x1000, v253
	v_mov_b32_e32 v255, 0x358637bd
	v_xor_b32_e32 v128, 1, v142
	v_lshlrev_b32_e32 v244, 2, v128
	v_xor_b32_e32 v128, 2, v142
	v_lshlrev_b32_e32 v245, 2, v128
	v_xor_b32_e32 v128, 4, v142
	v_lshlrev_b32_e32 v246, 2, v128
	v_xor_b32_e32 v128, 8, v142
	v_lshlrev_b32_e32 v247, 2, v128
	v_xor_b32_e32 v128, 16, v142
	v_lshlrev_b32_e32 v248, 2, v128
	v_xor_b32_e32 v128, 32, v142
	v_lshlrev_b32_e32 v249, 2, v128
	s_add_u32 s0, s0, 0x2000
	s_addc_u32 s1, s1, 0
	global_load_dwordx4 v[0:3], v253, s[0:1] offset:0
	global_load_dwordx4 v[4:7], v253, s[0:1] offset:1024
	global_load_dwordx4 v[8:11], v253, s[0:1] offset:2048
	global_load_dwordx4 v[12:15], v253, s[0:1] offset:3072
	global_load_dwordx4 v[16:19], v254, s[0:1] offset:0
	global_load_dwordx4 v[20:23], v254, s[0:1] offset:1024
	global_load_dwordx4 v[24:27], v254, s[0:1] offset:2048
	global_load_dwordx4 v[28:31], v254, s[0:1] offset:3072
	s_ashr_i32 s97, s96, 31
	s_lshl_b64 s[4:5], s[96:97], 12
	s_add_u32 s0, s6, s4
	s_addc_u32 s1, s7, s5
	s_add_u32 s2, s40, s4
	s_addc_u32 s3, s41, s5
	global_load_dwordx2 v[32:33], v252, s[0:1] offset:0 nt
	global_load_dwordx2 v[34:35], v252, s[0:1] offset:512 nt
	global_load_dwordx2 v[36:37], v252, s[0:1] offset:1024 nt
	global_load_dwordx2 v[38:39], v252, s[0:1] offset:1536 nt
	global_load_dwordx2 v[40:41], v252, s[0:1] offset:2048 nt
	global_load_dwordx2 v[42:43], v252, s[0:1] offset:2560 nt
	global_load_dwordx2 v[44:45], v252, s[0:1] offset:3072 nt
	global_load_dwordx2 v[46:47], v252, s[0:1] offset:3584 nt
	global_load_dwordx2 v[48:49], v252, s[2:3] offset:0 nt
	global_load_dwordx2 v[50:51], v252, s[2:3] offset:512 nt
	global_load_dwordx2 v[52:53], v252, s[2:3] offset:1024 nt
	global_load_dwordx2 v[54:55], v252, s[2:3] offset:1536 nt
	global_load_dwordx2 v[56:57], v252, s[2:3] offset:2048 nt
	global_load_dwordx2 v[58:59], v252, s[2:3] offset:2560 nt
	global_load_dwordx2 v[60:61], v252, s[2:3] offset:3072 nt
	global_load_dwordx2 v[62:63], v252, s[2:3] offset:3584 nt
	s_add_u32 s0, s0, 0x800000
	s_addc_u32 s1, s1, 0
	s_add_u32 s2, s2, 0x800000
	s_addc_u32 s3, s3, 0
	global_load_dwordx2 v[64:65], v252, s[0:1] offset:0 nt
	global_load_dwordx2 v[66:67], v252, s[0:1] offset:512 nt
	global_load_dwordx2 v[68:69], v252, s[0:1] offset:1024 nt
	global_load_dwordx2 v[70:71], v252, s[0:1] offset:1536 nt
	global_load_dwordx2 v[72:73], v252, s[0:1] offset:2048 nt
	global_load_dwordx2 v[74:75], v252, s[0:1] offset:2560 nt
	global_load_dwordx2 v[76:77], v252, s[0:1] offset:3072 nt
	global_load_dwordx2 v[78:79], v252, s[0:1] offset:3584 nt
	global_load_dwordx2 v[80:81], v252, s[2:3] offset:0 nt
	global_load_dwordx2 v[82:83], v252, s[2:3] offset:512 nt
	global_load_dwordx2 v[84:85], v252, s[2:3] offset:1024 nt
	global_load_dwordx2 v[86:87], v252, s[2:3] offset:1536 nt
	global_load_dwordx2 v[88:89], v252, s[2:3] offset:2048 nt
	global_load_dwordx2 v[90:91], v252, s[2:3] offset:2560 nt
	global_load_dwordx2 v[92:93], v252, s[2:3] offset:3072 nt
	global_load_dwordx2 v[94:95], v252, s[2:3] offset:3584 nt
	s_add_u32 s0, s0, 0x800000
	s_addc_u32 s1, s1, 0
	s_add_u32 s2, s2, 0x800000
	s_addc_u32 s3, s3, 0
	global_load_dwordx2 v[96:97], v252, s[0:1] offset:0 nt
	global_load_dwordx2 v[98:99], v252, s[0:1] offset:512 nt
	global_load_dwordx2 v[100:101], v252, s[0:1] offset:1024 nt
	global_load_dwordx2 v[102:103], v252, s[0:1] offset:1536 nt
	global_load_dwordx2 v[104:105], v252, s[0:1] offset:2048 nt
	global_load_dwordx2 v[106:107], v252, s[0:1] offset:2560 nt
	global_load_dwordx2 v[108:109], v252, s[0:1] offset:3072 nt
	global_load_dwordx2 v[110:111], v252, s[0:1] offset:3584 nt
	global_load_dwordx2 v[112:113], v252, s[2:3] offset:0 nt
	global_load_dwordx2 v[114:115], v252, s[2:3] offset:512 nt
	global_load_dwordx2 v[116:117], v252, s[2:3] offset:1024 nt
	global_load_dwordx2 v[118:119], v252, s[2:3] offset:1536 nt
	global_load_dwordx2 v[120:121], v252, s[2:3] offset:2048 nt
	global_load_dwordx2 v[122:123], v252, s[2:3] offset:2560 nt
	global_load_dwordx2 v[124:125], v252, s[2:3] offset:3072 nt
	global_load_dwordx2 v[126:127], v252, s[2:3] offset:3584 nt
	s_add_u32 s0, s0, 0x800000
	s_addc_u32 s1, s1, 0
	s_add_u32 s2, s2, 0x800000
	s_addc_u32 s3, s3, 0
	s_lshl_b64 s[4:5], s[96:97], 13
	s_add_u32 s4, s68, s4
	s_addc_u32 s5, s69, s5
	v_mov_b32_e32 v250, v253
	v_mov_b32_e32 v251, 0
	v_lshl_add_u64 v[250:251], s[4:5], 0, v[250:251]
	s_mov_b64 s[12:13], 0x1000000
	s_mov_b64 s[14:15], 0x1000
	s_mov_b32 s10, 0x800000
	s_waitcnt vmcnt(32)
	v_lshlrev_b32_e32 v208, 16, v48
	v_and_b32_e32 v209, 0xffff0000, v48
	v_lshlrev_b32_e32 v210, 16, v49
	v_and_b32_e32 v211, 0xffff0000, v49
	v_lshlrev_b32_e32 v212, 16, v50
	v_and_b32_e32 v213, 0xffff0000, v50
	v_lshlrev_b32_e32 v214, 16, v51
	v_and_b32_e32 v215, 0xffff0000, v51
	v_lshlrev_b32_e32 v216, 16, v52
	v_and_b32_e32 v217, 0xffff0000, v52
	v_lshlrev_b32_e32 v218, 16, v53
	v_and_b32_e32 v219, 0xffff0000, v53
	v_lshlrev_b32_e32 v220, 16, v54
	v_and_b32_e32 v221, 0xffff0000, v54
	v_lshlrev_b32_e32 v222, 16, v55
	v_and_b32_e32 v223, 0xffff0000, v55
	v_lshlrev_b32_e32 v224, 16, v56
	v_and_b32_e32 v225, 0xffff0000, v56
	v_lshlrev_b32_e32 v226, 16, v57
	v_and_b32_e32 v227, 0xffff0000, v57
	v_lshlrev_b32_e32 v228, 16, v58
	v_and_b32_e32 v229, 0xffff0000, v58
	v_lshlrev_b32_e32 v230, 16, v59
	v_and_b32_e32 v231, 0xffff0000, v59
	v_lshlrev_b32_e32 v232, 16, v60
	v_and_b32_e32 v233, 0xffff0000, v60
	v_lshlrev_b32_e32 v234, 16, v61
	v_and_b32_e32 v235, 0xffff0000, v61
	v_lshlrev_b32_e32 v236, 16, v62
	v_and_b32_e32 v237, 0xffff0000, v62
	v_lshlrev_b32_e32 v238, 16, v63
	v_and_b32_e32 v239, 0xffff0000, v63
	v_mul_f32_e32 v128, v208, v208
	v_fmac_f32_e32 v128, v209, v209
	v_mul_f32_e32 v129, v210, v210
	v_fmac_f32_e32 v129, v211, v211
	v_add_f32_e32 v128, v128, v129
	v_mul_f32_e32 v129, v212, v212
	v_fmac_f32_e32 v129, v213, v213
	v_mul_f32_e32 v132, v214, v214
	v_fmac_f32_e32 v132, v215, v215
	v_add_f32_e32 v129, v129, v132
	v_add_f32_e32 v128, v128, v129
	v_mul_f32_e32 v129, v216, v216
	v_fmac_f32_e32 v129, v217, v217
	v_mul_f32_e32 v132, v218, v218
	v_fmac_f32_e32 v132, v219, v219
	v_add_f32_e32 v129, v129, v132
	v_add_f32_e32 v128, v128, v129
	v_mul_f32_e32 v129, v220, v220
	v_fmac_f32_e32 v129, v221, v221
	v_mul_f32_e32 v132, v222, v222
	v_fmac_f32_e32 v132, v223, v223
	v_add_f32_e32 v129, v129, v132
	v_add_f32_e32 v128, v128, v129
	v_mul_f32_e32 v129, v224, v224
	v_fmac_f32_e32 v129, v225, v225
	v_mul_f32_e32 v132, v226, v226
	v_fmac_f32_e32 v132, v227, v227
	v_add_f32_e32 v129, v129, v132
	v_add_f32_e32 v128, v128, v129
	v_mul_f32_e32 v129, v228, v228
	v_fmac_f32_e32 v129, v229, v229
	v_mul_f32_e32 v132, v230, v230
	v_fmac_f32_e32 v132, v231, v231
	v_add_f32_e32 v129, v129, v132
	v_add_f32_e32 v128, v128, v129
	v_mul_f32_e32 v129, v232, v232
	v_fmac_f32_e32 v129, v233, v233
	v_mul_f32_e32 v132, v234, v234
	v_fmac_f32_e32 v132, v235, v235
	v_add_f32_e32 v129, v129, v132
	v_add_f32_e32 v128, v128, v129
	v_mul_f32_e32 v129, v236, v236
	v_fmac_f32_e32 v129, v237, v237
	v_mul_f32_e32 v132, v238, v238
	v_fmac_f32_e32 v132, v239, v239
	v_add_f32_e32 v129, v129, v132
	v_add_f32_e32 v128, v128, v129
	ds_bpermute_b32 v129, v244, v128
	s_waitcnt lgkmcnt(0)
	v_add_f32_e32 v128, v128, v129
	ds_bpermute_b32 v129, v245, v128
	s_waitcnt lgkmcnt(0)
	v_add_f32_e32 v128, v128, v129
	ds_bpermute_b32 v129, v246, v128
	s_waitcnt lgkmcnt(0)
	v_add_f32_e32 v128, v128, v129
	ds_bpermute_b32 v129, v247, v128
	s_waitcnt lgkmcnt(0)
	v_add_f32_e32 v128, v128, v129
	ds_bpermute_b32 v129, v248, v128
	s_waitcnt lgkmcnt(0)
	v_add_f32_e32 v128, v128, v129
	ds_bpermute_b32 v129, v249, v128
	s_waitcnt lgkmcnt(0)
	v_add_f32_e32 v128, v128, v129
	v_fmamk_f32 v128, v128, 0x3a000000, v255
	v_mul_f32_e32 v129, 0x4b800000, v128
	v_cmp_gt_f32_e32 vcc, s10, v128
	s_nop 1
	v_cndmask_b32_e32 v128, v128, v129, vcc
	v_rsq_f32_e32 v128, v128
	s_nop 0
	v_mul_f32_e32 v129, 0x45800000, v128
	v_cndmask_b32_e32 v130, v128, v129, vcc
	v_lshl_add_u64 v[140:141], v[250:251], 0, s[14:15]
	v_lshlrev_b32_e32 v136, 16, v32
	v_and_b32_e32 v137, 0xffff0000, v32
	v_lshlrev_b32_e32 v138, 16, v33
	v_and_b32_e32 v139, 0xffff0000, v33
	v_pk_mul_f32 v[208:209], v[130:131], v[208:209] op_sel_hi:[0,1]
	v_pk_fma_f32 v[208:209], v[0:1], v[208:209], v[136:137]
	v_pk_mul_f32 v[210:211], v[130:131], v[210:211] op_sel_hi:[0,1]
	v_pk_fma_f32 v[210:211], v[2:3], v[210:211], v[138:139]
	global_store_dwordx4 v[250:251], v[208:211], off offset:0 nt
	v_lshlrev_b32_e32 v136, 16, v34
	v_and_b32_e32 v137, 0xffff0000, v34
	v_lshlrev_b32_e32 v138, 16, v35
	v_and_b32_e32 v139, 0xffff0000, v35
	v_pk_mul_f32 v[212:213], v[130:131], v[212:213] op_sel_hi:[0,1]
	v_pk_fma_f32 v[212:213], v[4:5], v[212:213], v[136:137]
	v_pk_mul_f32 v[214:215], v[130:131], v[214:215] op_sel_hi:[0,1]
	v_pk_fma_f32 v[214:215], v[6:7], v[214:215], v[138:139]
	global_store_dwordx4 v[250:251], v[212:215], off offset:1024 nt
	v_lshlrev_b32_e32 v136, 16, v36
	v_and_b32_e32 v137, 0xffff0000, v36
	v_lshlrev_b32_e32 v138, 16, v37
	v_and_b32_e32 v139, 0xffff0000, v37
	v_pk_mul_f32 v[216:217], v[130:131], v[216:217] op_sel_hi:[0,1]
	v_pk_fma_f32 v[216:217], v[8:9], v[216:217], v[136:137]
	v_pk_mul_f32 v[218:219], v[130:131], v[218:219] op_sel_hi:[0,1]
	v_pk_fma_f32 v[218:219], v[10:11], v[218:219], v[138:139]
	global_store_dwordx4 v[250:251], v[216:219], off offset:2048 nt
	v_lshlrev_b32_e32 v136, 16, v38
	v_and_b32_e32 v137, 0xffff0000, v38
	v_lshlrev_b32_e32 v138, 16, v39
	v_and_b32_e32 v139, 0xffff0000, v39
	v_pk_mul_f32 v[220:221], v[130:131], v[220:221] op_sel_hi:[0,1]
	v_pk_fma_f32 v[220:221], v[12:13], v[220:221], v[136:137]
	v_pk_mul_f32 v[222:223], v[130:131], v[222:223] op_sel_hi:[0,1]
	v_pk_fma_f32 v[222:223], v[14:15], v[222:223], v[138:139]
	global_store_dwordx4 v[250:251], v[220:223], off offset:3072 nt
	v_lshlrev_b32_e32 v136, 16, v40
	v_and_b32_e32 v137, 0xffff0000, v40
	v_lshlrev_b32_e32 v138, 16, v41
	v_and_b32_e32 v139, 0xffff0000, v41
	v_pk_mul_f32 v[224:225], v[130:131], v[224:225] op_sel_hi:[0,1]
	v_pk_fma_f32 v[224:225], v[16:17], v[224:225], v[136:137]
	v_pk_mul_f32 v[226:227], v[130:131], v[226:227] op_sel_hi:[0,1]
	v_pk_fma_f32 v[226:227], v[18:19], v[226:227], v[138:139]
	global_store_dwordx4 v[140:141], v[224:227], off offset:0 nt
	v_lshlrev_b32_e32 v136, 16, v42
	v_and_b32_e32 v137, 0xffff0000, v42
	v_lshlrev_b32_e32 v138, 16, v43
	v_and_b32_e32 v139, 0xffff0000, v43
	v_pk_mul_f32 v[228:229], v[130:131], v[228:229] op_sel_hi:[0,1]
	v_pk_fma_f32 v[228:229], v[20:21], v[228:229], v[136:137]
	v_pk_mul_f32 v[230:231], v[130:131], v[230:231] op_sel_hi:[0,1]
	v_pk_fma_f32 v[230:231], v[22:23], v[230:231], v[138:139]
	global_store_dwordx4 v[140:141], v[228:231], off offset:1024 nt
	v_lshlrev_b32_e32 v136, 16, v44
	v_and_b32_e32 v137, 0xffff0000, v44
	v_lshlrev_b32_e32 v138, 16, v45
	v_and_b32_e32 v139, 0xffff0000, v45
	v_pk_mul_f32 v[232:233], v[130:131], v[232:233] op_sel_hi:[0,1]
	v_pk_fma_f32 v[232:233], v[24:25], v[232:233], v[136:137]
	v_pk_mul_f32 v[234:235], v[130:131], v[234:235] op_sel_hi:[0,1]
	v_pk_fma_f32 v[234:235], v[26:27], v[234:235], v[138:139]
	global_store_dwordx4 v[140:141], v[232:235], off offset:2048 nt
	v_lshlrev_b32_e32 v136, 16, v46
	v_and_b32_e32 v137, 0xffff0000, v46
	v_lshlrev_b32_e32 v138, 16, v47
	v_and_b32_e32 v139, 0xffff0000, v47
	v_pk_mul_f32 v[236:237], v[130:131], v[236:237] op_sel_hi:[0,1]
	v_pk_fma_f32 v[236:237], v[28:29], v[236:237], v[136:137]
	v_pk_mul_f32 v[238:239], v[130:131], v[238:239] op_sel_hi:[0,1]
	v_pk_fma_f32 v[238:239], v[30:31], v[238:239], v[138:139]
	global_store_dwordx4 v[140:141], v[236:239], off offset:3072 nt
	v_lshl_add_u64 v[250:251], v[250:251], 0, s[12:13]
	global_load_dwordx2 v[144:145], v252, s[0:1] offset:0 nt
	global_load_dwordx2 v[146:147], v252, s[0:1] offset:512 nt
	global_load_dwordx2 v[148:149], v252, s[0:1] offset:1024 nt
	global_load_dwordx2 v[150:151], v252, s[0:1] offset:1536 nt
	global_load_dwordx2 v[152:153], v252, s[0:1] offset:2048 nt
	global_load_dwordx2 v[154:155], v252, s[0:1] offset:2560 nt
	global_load_dwordx2 v[156:157], v252, s[0:1] offset:3072 nt
	global_load_dwordx2 v[158:159], v252, s[0:1] offset:3584 nt
	global_load_dwordx2 v[160:161], v252, s[2:3] offset:0 nt
	global_load_dwordx2 v[162:163], v252, s[2:3] offset:512 nt
	global_load_dwordx2 v[164:165], v252, s[2:3] offset:1024 nt
	global_load_dwordx2 v[166:167], v252, s[2:3] offset:1536 nt
	global_load_dwordx2 v[168:169], v252, s[2:3] offset:2048 nt
	global_load_dwordx2 v[170:171], v252, s[2:3] offset:2560 nt
	global_load_dwordx2 v[172:173], v252, s[2:3] offset:3072 nt
	global_load_dwordx2 v[174:175], v252, s[2:3] offset:3584 nt
	s_add_u32 s0, s0, 0x800000
	s_addc_u32 s1, s1, 0
	s_add_u32 s2, s2, 0x800000
	s_addc_u32 s3, s3, 0
	s_waitcnt vmcnt(40)
	v_lshlrev_b32_e32 v208, 16, v80
	v_and_b32_e32 v209, 0xffff0000, v80
	v_lshlrev_b32_e32 v210, 16, v81
	v_and_b32_e32 v211, 0xffff0000, v81
	v_lshlrev_b32_e32 v212, 16, v82
	v_and_b32_e32 v213, 0xffff0000, v82
	v_lshlrev_b32_e32 v214, 16, v83
	v_and_b32_e32 v215, 0xffff0000, v83
	v_lshlrev_b32_e32 v216, 16, v84
	v_and_b32_e32 v217, 0xffff0000, v84
	v_lshlrev_b32_e32 v218, 16, v85
	v_and_b32_e32 v219, 0xffff0000, v85
	v_lshlrev_b32_e32 v220, 16, v86
	v_and_b32_e32 v221, 0xffff0000, v86
	v_lshlrev_b32_e32 v222, 16, v87
	v_and_b32_e32 v223, 0xffff0000, v87
	v_lshlrev_b32_e32 v224, 16, v88
	v_and_b32_e32 v225, 0xffff0000, v88
	v_lshlrev_b32_e32 v226, 16, v89
	v_and_b32_e32 v227, 0xffff0000, v89
	v_lshlrev_b32_e32 v228, 16, v90
	v_and_b32_e32 v229, 0xffff0000, v90
	v_lshlrev_b32_e32 v230, 16, v91
	v_and_b32_e32 v231, 0xffff0000, v91
	v_lshlrev_b32_e32 v232, 16, v92
	v_and_b32_e32 v233, 0xffff0000, v92
	v_lshlrev_b32_e32 v234, 16, v93
	v_and_b32_e32 v235, 0xffff0000, v93
	v_lshlrev_b32_e32 v236, 16, v94
	v_and_b32_e32 v237, 0xffff0000, v94
	v_lshlrev_b32_e32 v238, 16, v95
	v_and_b32_e32 v239, 0xffff0000, v95
	v_mul_f32_e32 v128, v208, v208
	v_fmac_f32_e32 v128, v209, v209
	v_mul_f32_e32 v129, v210, v210
	v_fmac_f32_e32 v129, v211, v211
	v_add_f32_e32 v128, v128, v129
	v_mul_f32_e32 v129, v212, v212
	v_fmac_f32_e32 v129, v213, v213
	v_mul_f32_e32 v132, v214, v214
	v_fmac_f32_e32 v132, v215, v215
	v_add_f32_e32 v129, v129, v132
	v_add_f32_e32 v128, v128, v129
	v_mul_f32_e32 v129, v216, v216
	v_fmac_f32_e32 v129, v217, v217
	v_mul_f32_e32 v132, v218, v218
	v_fmac_f32_e32 v132, v219, v219
	v_add_f32_e32 v129, v129, v132
	v_add_f32_e32 v128, v128, v129
	v_mul_f32_e32 v129, v220, v220
	v_fmac_f32_e32 v129, v221, v221
	v_mul_f32_e32 v132, v222, v222
	v_fmac_f32_e32 v132, v223, v223
	v_add_f32_e32 v129, v129, v132
	v_add_f32_e32 v128, v128, v129
	v_mul_f32_e32 v129, v224, v224
	v_fmac_f32_e32 v129, v225, v225
	v_mul_f32_e32 v132, v226, v226
	v_fmac_f32_e32 v132, v227, v227
	v_add_f32_e32 v129, v129, v132
	v_add_f32_e32 v128, v128, v129
	v_mul_f32_e32 v129, v228, v228
	v_fmac_f32_e32 v129, v229, v229
	v_mul_f32_e32 v132, v230, v230
	v_fmac_f32_e32 v132, v231, v231
	v_add_f32_e32 v129, v129, v132
	v_add_f32_e32 v128, v128, v129
	v_mul_f32_e32 v129, v232, v232
	v_fmac_f32_e32 v129, v233, v233
	v_mul_f32_e32 v132, v234, v234
	v_fmac_f32_e32 v132, v235, v235
	v_add_f32_e32 v129, v129, v132
	v_add_f32_e32 v128, v128, v129
	v_mul_f32_e32 v129, v236, v236
	v_fmac_f32_e32 v129, v237, v237
	v_mul_f32_e32 v132, v238, v238
	v_fmac_f32_e32 v132, v239, v239
	v_add_f32_e32 v129, v129, v132
	v_add_f32_e32 v128, v128, v129
	ds_bpermute_b32 v129, v244, v128
	s_waitcnt lgkmcnt(0)
	v_add_f32_e32 v128, v128, v129
	ds_bpermute_b32 v129, v245, v128
	s_waitcnt lgkmcnt(0)
	v_add_f32_e32 v128, v128, v129
	ds_bpermute_b32 v129, v246, v128
	s_waitcnt lgkmcnt(0)
	v_add_f32_e32 v128, v128, v129
	ds_bpermute_b32 v129, v247, v128
	s_waitcnt lgkmcnt(0)
	v_add_f32_e32 v128, v128, v129
	ds_bpermute_b32 v129, v248, v128
	s_waitcnt lgkmcnt(0)
	v_add_f32_e32 v128, v128, v129
	ds_bpermute_b32 v129, v249, v128
	s_waitcnt lgkmcnt(0)
	v_add_f32_e32 v128, v128, v129
	v_fmamk_f32 v128, v128, 0x3a000000, v255
	v_mul_f32_e32 v129, 0x4b800000, v128
	v_cmp_gt_f32_e32 vcc, s10, v128
	s_nop 1
	v_cndmask_b32_e32 v128, v128, v129, vcc
	v_rsq_f32_e32 v128, v128
	s_nop 0
	v_mul_f32_e32 v129, 0x45800000, v128
	v_cndmask_b32_e32 v130, v128, v129, vcc
	v_lshl_add_u64 v[140:141], v[250:251], 0, s[14:15]
	v_lshlrev_b32_e32 v136, 16, v64
	v_and_b32_e32 v137, 0xffff0000, v64
	v_lshlrev_b32_e32 v138, 16, v65
	v_and_b32_e32 v139, 0xffff0000, v65
	v_pk_mul_f32 v[208:209], v[130:131], v[208:209] op_sel_hi:[0,1]
	v_pk_fma_f32 v[208:209], v[0:1], v[208:209], v[136:137]
	v_pk_mul_f32 v[210:211], v[130:131], v[210:211] op_sel_hi:[0,1]
	v_pk_fma_f32 v[210:211], v[2:3], v[210:211], v[138:139]
	global_store_dwordx4 v[250:251], v[208:211], off offset:0 nt
	v_lshlrev_b32_e32 v136, 16, v66
	v_and_b32_e32 v137, 0xffff0000, v66
	v_lshlrev_b32_e32 v138, 16, v67
	v_and_b32_e32 v139, 0xffff0000, v67
	v_pk_mul_f32 v[212:213], v[130:131], v[212:213] op_sel_hi:[0,1]
	v_pk_fma_f32 v[212:213], v[4:5], v[212:213], v[136:137]
	v_pk_mul_f32 v[214:215], v[130:131], v[214:215] op_sel_hi:[0,1]
	v_pk_fma_f32 v[214:215], v[6:7], v[214:215], v[138:139]
	global_store_dwordx4 v[250:251], v[212:215], off offset:1024 nt
	v_lshlrev_b32_e32 v136, 16, v68
	v_and_b32_e32 v137, 0xffff0000, v68
	v_lshlrev_b32_e32 v138, 16, v69
	v_and_b32_e32 v139, 0xffff0000, v69
	v_pk_mul_f32 v[216:217], v[130:131], v[216:217] op_sel_hi:[0,1]
	v_pk_fma_f32 v[216:217], v[8:9], v[216:217], v[136:137]
	v_pk_mul_f32 v[218:219], v[130:131], v[218:219] op_sel_hi:[0,1]
	v_pk_fma_f32 v[218:219], v[10:11], v[218:219], v[138:139]
	global_store_dwordx4 v[250:251], v[216:219], off offset:2048 nt
	v_lshlrev_b32_e32 v136, 16, v70
	v_and_b32_e32 v137, 0xffff0000, v70
	v_lshlrev_b32_e32 v138, 16, v71
	v_and_b32_e32 v139, 0xffff0000, v71
	v_pk_mul_f32 v[220:221], v[130:131], v[220:221] op_sel_hi:[0,1]
	v_pk_fma_f32 v[220:221], v[12:13], v[220:221], v[136:137]
	v_pk_mul_f32 v[222:223], v[130:131], v[222:223] op_sel_hi:[0,1]
	v_pk_fma_f32 v[222:223], v[14:15], v[222:223], v[138:139]
	global_store_dwordx4 v[250:251], v[220:223], off offset:3072 nt
	v_lshlrev_b32_e32 v136, 16, v72
	v_and_b32_e32 v137, 0xffff0000, v72
	v_lshlrev_b32_e32 v138, 16, v73
	v_and_b32_e32 v139, 0xffff0000, v73
	v_pk_mul_f32 v[224:225], v[130:131], v[224:225] op_sel_hi:[0,1]
	v_pk_fma_f32 v[224:225], v[16:17], v[224:225], v[136:137]
	v_pk_mul_f32 v[226:227], v[130:131], v[226:227] op_sel_hi:[0,1]
	v_pk_fma_f32 v[226:227], v[18:19], v[226:227], v[138:139]
	global_store_dwordx4 v[140:141], v[224:227], off offset:0 nt
	v_lshlrev_b32_e32 v136, 16, v74
	v_and_b32_e32 v137, 0xffff0000, v74
	v_lshlrev_b32_e32 v138, 16, v75
	v_and_b32_e32 v139, 0xffff0000, v75
	v_pk_mul_f32 v[228:229], v[130:131], v[228:229] op_sel_hi:[0,1]
	v_pk_fma_f32 v[228:229], v[20:21], v[228:229], v[136:137]
	v_pk_mul_f32 v[230:231], v[130:131], v[230:231] op_sel_hi:[0,1]
	v_pk_fma_f32 v[230:231], v[22:23], v[230:231], v[138:139]
	global_store_dwordx4 v[140:141], v[228:231], off offset:1024 nt
	v_lshlrev_b32_e32 v136, 16, v76
	v_and_b32_e32 v137, 0xffff0000, v76
	v_lshlrev_b32_e32 v138, 16, v77
	v_and_b32_e32 v139, 0xffff0000, v77
	v_pk_mul_f32 v[232:233], v[130:131], v[232:233] op_sel_hi:[0,1]
	v_pk_fma_f32 v[232:233], v[24:25], v[232:233], v[136:137]
	v_pk_mul_f32 v[234:235], v[130:131], v[234:235] op_sel_hi:[0,1]
	v_pk_fma_f32 v[234:235], v[26:27], v[234:235], v[138:139]
	global_store_dwordx4 v[140:141], v[232:235], off offset:2048 nt
	v_lshlrev_b32_e32 v136, 16, v78
	v_and_b32_e32 v137, 0xffff0000, v78
	v_lshlrev_b32_e32 v138, 16, v79
	v_and_b32_e32 v139, 0xffff0000, v79
	v_pk_mul_f32 v[236:237], v[130:131], v[236:237] op_sel_hi:[0,1]
	v_pk_fma_f32 v[236:237], v[28:29], v[236:237], v[136:137]
	v_pk_mul_f32 v[238:239], v[130:131], v[238:239] op_sel_hi:[0,1]
	v_pk_fma_f32 v[238:239], v[30:31], v[238:239], v[138:139]
	global_store_dwordx4 v[140:141], v[236:239], off offset:3072 nt
	v_lshl_add_u64 v[250:251], v[250:251], 0, s[12:13]
	s_waitcnt vmcnt(32)
	s_cmpk_gt_i32 s96, 0x1ff
	s_cbranch_scc1 .Lp15_no5a
	global_load_dwordx2 v[176:177], v252, s[0:1] offset:0 nt
	global_load_dwordx2 v[178:179], v252, s[0:1] offset:512 nt
	global_load_dwordx2 v[180:181], v252, s[0:1] offset:1024 nt
	global_load_dwordx2 v[182:183], v252, s[0:1] offset:1536 nt
	global_load_dwordx2 v[184:185], v252, s[0:1] offset:2048 nt
	global_load_dwordx2 v[186:187], v252, s[0:1] offset:2560 nt
	global_load_dwordx2 v[188:189], v252, s[0:1] offset:3072 nt
	global_load_dwordx2 v[190:191], v252, s[0:1] offset:3584 nt
	global_load_dwordx2 v[192:193], v252, s[2:3] offset:0 nt
	global_load_dwordx2 v[194:195], v252, s[2:3] offset:512 nt
	global_load_dwordx2 v[196:197], v252, s[2:3] offset:1024 nt
	global_load_dwordx2 v[198:199], v252, s[2:3] offset:1536 nt
	global_load_dwordx2 v[200:201], v252, s[2:3] offset:2048 nt
	global_load_dwordx2 v[202:203], v252, s[2:3] offset:2560 nt
	global_load_dwordx2 v[204:205], v252, s[2:3] offset:3072 nt
	global_load_dwordx2 v[206:207], v252, s[2:3] offset:3584 nt
	s_add_u32 s0, s0, 0x800000
	s_addc_u32 s1, s1, 0
	s_add_u32 s2, s2, 0x800000
	s_addc_u32 s3, s3, 0
.Lp15_no5a:
	v_lshlrev_b32_e32 v208, 16, v112
	v_and_b32_e32 v209, 0xffff0000, v112
	v_lshlrev_b32_e32 v210, 16, v113
	v_and_b32_e32 v211, 0xffff0000, v113
	v_lshlrev_b32_e32 v212, 16, v114
	v_and_b32_e32 v213, 0xffff0000, v114
	v_lshlrev_b32_e32 v214, 16, v115
	v_and_b32_e32 v215, 0xffff0000, v115
	v_lshlrev_b32_e32 v216, 16, v116
	v_and_b32_e32 v217, 0xffff0000, v116
	v_lshlrev_b32_e32 v218, 16, v117
	v_and_b32_e32 v219, 0xffff0000, v117
	v_lshlrev_b32_e32 v220, 16, v118
	v_and_b32_e32 v221, 0xffff0000, v118
	v_lshlrev_b32_e32 v222, 16, v119
	v_and_b32_e32 v223, 0xffff0000, v119
	v_lshlrev_b32_e32 v224, 16, v120
	v_and_b32_e32 v225, 0xffff0000, v120
	v_lshlrev_b32_e32 v226, 16, v121
	v_and_b32_e32 v227, 0xffff0000, v121
	v_lshlrev_b32_e32 v228, 16, v122
	v_and_b32_e32 v229, 0xffff0000, v122
	v_lshlrev_b32_e32 v230, 16, v123
	v_and_b32_e32 v231, 0xffff0000, v123
	v_lshlrev_b32_e32 v232, 16, v124
	v_and_b32_e32 v233, 0xffff0000, v124
	v_lshlrev_b32_e32 v234, 16, v125
	v_and_b32_e32 v235, 0xffff0000, v125
	v_lshlrev_b32_e32 v236, 16, v126
	v_and_b32_e32 v237, 0xffff0000, v126
	v_lshlrev_b32_e32 v238, 16, v127
	v_and_b32_e32 v239, 0xffff0000, v127
	v_mul_f32_e32 v128, v208, v208
	v_fmac_f32_e32 v128, v209, v209
	v_mul_f32_e32 v129, v210, v210
	v_fmac_f32_e32 v129, v211, v211
	v_add_f32_e32 v128, v128, v129
	v_mul_f32_e32 v129, v212, v212
	v_fmac_f32_e32 v129, v213, v213
	v_mul_f32_e32 v132, v214, v214
	v_fmac_f32_e32 v132, v215, v215
	v_add_f32_e32 v129, v129, v132
	v_add_f32_e32 v128, v128, v129
	v_mul_f32_e32 v129, v216, v216
	v_fmac_f32_e32 v129, v217, v217
	v_mul_f32_e32 v132, v218, v218
	v_fmac_f32_e32 v132, v219, v219
	v_add_f32_e32 v129, v129, v132
	v_add_f32_e32 v128, v128, v129
	v_mul_f32_e32 v129, v220, v220
	v_fmac_f32_e32 v129, v221, v221
	v_mul_f32_e32 v132, v222, v222
	v_fmac_f32_e32 v132, v223, v223
	v_add_f32_e32 v129, v129, v132
	v_add_f32_e32 v128, v128, v129
	v_mul_f32_e32 v129, v224, v224
	v_fmac_f32_e32 v129, v225, v225
	v_mul_f32_e32 v132, v226, v226
	v_fmac_f32_e32 v132, v227, v227
	v_add_f32_e32 v129, v129, v132
	v_add_f32_e32 v128, v128, v129
	v_mul_f32_e32 v129, v228, v228
	v_fmac_f32_e32 v129, v229, v229
	v_mul_f32_e32 v132, v230, v230
	v_fmac_f32_e32 v132, v231, v231
	v_add_f32_e32 v129, v129, v132
	v_add_f32_e32 v128, v128, v129
	v_mul_f32_e32 v129, v232, v232
	v_fmac_f32_e32 v129, v233, v233
	v_mul_f32_e32 v132, v234, v234
	v_fmac_f32_e32 v132, v235, v235
	v_add_f32_e32 v129, v129, v132
	v_add_f32_e32 v128, v128, v129
	v_mul_f32_e32 v129, v236, v236
	v_fmac_f32_e32 v129, v237, v237
	v_mul_f32_e32 v132, v238, v238
	v_fmac_f32_e32 v132, v239, v239
	v_add_f32_e32 v129, v129, v132
	v_add_f32_e32 v128, v128, v129
	ds_bpermute_b32 v129, v244, v128
	s_waitcnt lgkmcnt(0)
	v_add_f32_e32 v128, v128, v129
	ds_bpermute_b32 v129, v245, v128
	s_waitcnt lgkmcnt(0)
	v_add_f32_e32 v128, v128, v129
	ds_bpermute_b32 v129, v246, v128
	s_waitcnt lgkmcnt(0)
	v_add_f32_e32 v128, v128, v129
	ds_bpermute_b32 v129, v247, v128
	s_waitcnt lgkmcnt(0)
	v_add_f32_e32 v128, v128, v129
	ds_bpermute_b32 v129, v248, v128
	s_waitcnt lgkmcnt(0)
	v_add_f32_e32 v128, v128, v129
	ds_bpermute_b32 v129, v249, v128
	s_waitcnt lgkmcnt(0)
	v_add_f32_e32 v128, v128, v129
	v_fmamk_f32 v128, v128, 0x3a000000, v255
	v_mul_f32_e32 v129, 0x4b800000, v128
	v_cmp_gt_f32_e32 vcc, s10, v128
	s_nop 1
	v_cndmask_b32_e32 v128, v128, v129, vcc
	v_rsq_f32_e32 v128, v128
	s_nop 0
	v_mul_f32_e32 v129, 0x45800000, v128
	v_cndmask_b32_e32 v130, v128, v129, vcc
	v_lshl_add_u64 v[140:141], v[250:251], 0, s[14:15]
	v_lshlrev_b32_e32 v136, 16, v96
	v_and_b32_e32 v137, 0xffff0000, v96
	v_lshlrev_b32_e32 v138, 16, v97
	v_and_b32_e32 v139, 0xffff0000, v97
	v_pk_mul_f32 v[208:209], v[130:131], v[208:209] op_sel_hi:[0,1]
	v_pk_fma_f32 v[208:209], v[0:1], v[208:209], v[136:137]
	v_pk_mul_f32 v[210:211], v[130:131], v[210:211] op_sel_hi:[0,1]
	v_pk_fma_f32 v[210:211], v[2:3], v[210:211], v[138:139]
	global_store_dwordx4 v[250:251], v[208:211], off offset:0 nt
	v_lshlrev_b32_e32 v136, 16, v98
	v_and_b32_e32 v137, 0xffff0000, v98
	v_lshlrev_b32_e32 v138, 16, v99
	v_and_b32_e32 v139, 0xffff0000, v99
	v_pk_mul_f32 v[212:213], v[130:131], v[212:213] op_sel_hi:[0,1]
	v_pk_fma_f32 v[212:213], v[4:5], v[212:213], v[136:137]
	v_pk_mul_f32 v[214:215], v[130:131], v[214:215] op_sel_hi:[0,1]
	v_pk_fma_f32 v[214:215], v[6:7], v[214:215], v[138:139]
	global_store_dwordx4 v[250:251], v[212:215], off offset:1024 nt
	v_lshlrev_b32_e32 v136, 16, v100
	v_and_b32_e32 v137, 0xffff0000, v100
	v_lshlrev_b32_e32 v138, 16, v101
	v_and_b32_e32 v139, 0xffff0000, v101
	v_pk_mul_f32 v[216:217], v[130:131], v[216:217] op_sel_hi:[0,1]
	v_pk_fma_f32 v[216:217], v[8:9], v[216:217], v[136:137]
	v_pk_mul_f32 v[218:219], v[130:131], v[218:219] op_sel_hi:[0,1]
	v_pk_fma_f32 v[218:219], v[10:11], v[218:219], v[138:139]
	global_store_dwordx4 v[250:251], v[216:219], off offset:2048 nt
	v_lshlrev_b32_e32 v136, 16, v102
	v_and_b32_e32 v137, 0xffff0000, v102
	v_lshlrev_b32_e32 v138, 16, v103
	v_and_b32_e32 v139, 0xffff0000, v103
	v_pk_mul_f32 v[220:221], v[130:131], v[220:221] op_sel_hi:[0,1]
	v_pk_fma_f32 v[220:221], v[12:13], v[220:221], v[136:137]
	v_pk_mul_f32 v[222:223], v[130:131], v[222:223] op_sel_hi:[0,1]
	v_pk_fma_f32 v[222:223], v[14:15], v[222:223], v[138:139]
	global_store_dwordx4 v[250:251], v[220:223], off offset:3072 nt
	v_lshlrev_b32_e32 v136, 16, v104
	v_and_b32_e32 v137, 0xffff0000, v104
	v_lshlrev_b32_e32 v138, 16, v105
	v_and_b32_e32 v139, 0xffff0000, v105
	v_pk_mul_f32 v[224:225], v[130:131], v[224:225] op_sel_hi:[0,1]
	v_pk_fma_f32 v[224:225], v[16:17], v[224:225], v[136:137]
	v_pk_mul_f32 v[226:227], v[130:131], v[226:227] op_sel_hi:[0,1]
	v_pk_fma_f32 v[226:227], v[18:19], v[226:227], v[138:139]
	global_store_dwordx4 v[140:141], v[224:227], off offset:0 nt
	v_lshlrev_b32_e32 v136, 16, v106
	v_and_b32_e32 v137, 0xffff0000, v106
	v_lshlrev_b32_e32 v138, 16, v107
	v_and_b32_e32 v139, 0xffff0000, v107
	v_pk_mul_f32 v[228:229], v[130:131], v[228:229] op_sel_hi:[0,1]
	v_pk_fma_f32 v[228:229], v[20:21], v[228:229], v[136:137]
	v_pk_mul_f32 v[230:231], v[130:131], v[230:231] op_sel_hi:[0,1]
	v_pk_fma_f32 v[230:231], v[22:23], v[230:231], v[138:139]
	global_store_dwordx4 v[140:141], v[228:231], off offset:1024 nt
	v_lshlrev_b32_e32 v136, 16, v108
	v_and_b32_e32 v137, 0xffff0000, v108
	v_lshlrev_b32_e32 v138, 16, v109
	v_and_b32_e32 v139, 0xffff0000, v109
	v_pk_mul_f32 v[232:233], v[130:131], v[232:233] op_sel_hi:[0,1]
	v_pk_fma_f32 v[232:233], v[24:25], v[232:233], v[136:137]
	v_pk_mul_f32 v[234:235], v[130:131], v[234:235] op_sel_hi:[0,1]
	v_pk_fma_f32 v[234:235], v[26:27], v[234:235], v[138:139]
	global_store_dwordx4 v[140:141], v[232:235], off offset:2048 nt
	v_lshlrev_b32_e32 v136, 16, v110
	v_and_b32_e32 v137, 0xffff0000, v110
	v_lshlrev_b32_e32 v138, 16, v111
	v_and_b32_e32 v139, 0xffff0000, v111
	v_pk_mul_f32 v[236:237], v[130:131], v[236:237] op_sel_hi:[0,1]
	v_pk_fma_f32 v[236:237], v[28:29], v[236:237], v[136:137]
	v_pk_mul_f32 v[238:239], v[130:131], v[238:239] op_sel_hi:[0,1]
	v_pk_fma_f32 v[238:239], v[30:31], v[238:239], v[138:139]
	global_store_dwordx4 v[140:141], v[236:239], off offset:3072 nt
	v_lshl_add_u64 v[250:251], v[250:251], 0, s[12:13]
	s_waitcnt vmcnt(16)
	v_lshlrev_b32_e32 v208, 16, v160
	v_and_b32_e32 v209, 0xffff0000, v160
	v_lshlrev_b32_e32 v210, 16, v161
	v_and_b32_e32 v211, 0xffff0000, v161
	v_lshlrev_b32_e32 v212, 16, v162
	v_and_b32_e32 v213, 0xffff0000, v162
	v_lshlrev_b32_e32 v214, 16, v163
	v_and_b32_e32 v215, 0xffff0000, v163
	v_lshlrev_b32_e32 v216, 16, v164
	v_and_b32_e32 v217, 0xffff0000, v164
	v_lshlrev_b32_e32 v218, 16, v165
	v_and_b32_e32 v219, 0xffff0000, v165
	v_lshlrev_b32_e32 v220, 16, v166
	v_and_b32_e32 v221, 0xffff0000, v166
	v_lshlrev_b32_e32 v222, 16, v167
	v_and_b32_e32 v223, 0xffff0000, v167
	v_lshlrev_b32_e32 v224, 16, v168
	v_and_b32_e32 v225, 0xffff0000, v168
	v_lshlrev_b32_e32 v226, 16, v169
	v_and_b32_e32 v227, 0xffff0000, v169
	v_lshlrev_b32_e32 v228, 16, v170
	v_and_b32_e32 v229, 0xffff0000, v170
	v_lshlrev_b32_e32 v230, 16, v171
	v_and_b32_e32 v231, 0xffff0000, v171
	v_lshlrev_b32_e32 v232, 16, v172
	v_and_b32_e32 v233, 0xffff0000, v172
	v_lshlrev_b32_e32 v234, 16, v173
	v_and_b32_e32 v235, 0xffff0000, v173
	v_lshlrev_b32_e32 v236, 16, v174
	v_and_b32_e32 v237, 0xffff0000, v174
	v_lshlrev_b32_e32 v238, 16, v175
	v_and_b32_e32 v239, 0xffff0000, v175
	v_mul_f32_e32 v128, v208, v208
	v_fmac_f32_e32 v128, v209, v209
	v_mul_f32_e32 v129, v210, v210
	v_fmac_f32_e32 v129, v211, v211
	v_add_f32_e32 v128, v128, v129
	v_mul_f32_e32 v129, v212, v212
	v_fmac_f32_e32 v129, v213, v213
	v_mul_f32_e32 v132, v214, v214
	v_fmac_f32_e32 v132, v215, v215
	v_add_f32_e32 v129, v129, v132
	v_add_f32_e32 v128, v128, v129
	v_mul_f32_e32 v129, v216, v216
	v_fmac_f32_e32 v129, v217, v217
	v_mul_f32_e32 v132, v218, v218
	v_fmac_f32_e32 v132, v219, v219
	v_add_f32_e32 v129, v129, v132
	v_add_f32_e32 v128, v128, v129
	v_mul_f32_e32 v129, v220, v220
	v_fmac_f32_e32 v129, v221, v221
	v_mul_f32_e32 v132, v222, v222
	v_fmac_f32_e32 v132, v223, v223
	v_add_f32_e32 v129, v129, v132
	v_add_f32_e32 v128, v128, v129
	v_mul_f32_e32 v129, v224, v224
	v_fmac_f32_e32 v129, v225, v225
	v_mul_f32_e32 v132, v226, v226
	v_fmac_f32_e32 v132, v227, v227
	v_add_f32_e32 v129, v129, v132
	v_add_f32_e32 v128, v128, v129
	v_mul_f32_e32 v129, v228, v228
	v_fmac_f32_e32 v129, v229, v229
	v_mul_f32_e32 v132, v230, v230
	v_fmac_f32_e32 v132, v231, v231
	v_add_f32_e32 v129, v129, v132
	v_add_f32_e32 v128, v128, v129
	v_mul_f32_e32 v129, v232, v232
	v_fmac_f32_e32 v129, v233, v233
	v_mul_f32_e32 v132, v234, v234
	v_fmac_f32_e32 v132, v235, v235
	v_add_f32_e32 v129, v129, v132
	v_add_f32_e32 v128, v128, v129
	v_mul_f32_e32 v129, v236, v236
	v_fmac_f32_e32 v129, v237, v237
	v_mul_f32_e32 v132, v238, v238
	v_fmac_f32_e32 v132, v239, v239
	v_add_f32_e32 v129, v129, v132
	v_add_f32_e32 v128, v128, v129
	ds_bpermute_b32 v129, v244, v128
	s_waitcnt lgkmcnt(0)
	v_add_f32_e32 v128, v128, v129
	ds_bpermute_b32 v129, v245, v128
	s_waitcnt lgkmcnt(0)
	v_add_f32_e32 v128, v128, v129
	ds_bpermute_b32 v129, v246, v128
	s_waitcnt lgkmcnt(0)
	v_add_f32_e32 v128, v128, v129
	ds_bpermute_b32 v129, v247, v128
	s_waitcnt lgkmcnt(0)
	v_add_f32_e32 v128, v128, v129
	ds_bpermute_b32 v129, v248, v128
	s_waitcnt lgkmcnt(0)
	v_add_f32_e32 v128, v128, v129
	ds_bpermute_b32 v129, v249, v128
	s_waitcnt lgkmcnt(0)
	v_add_f32_e32 v128, v128, v129
	v_fmamk_f32 v128, v128, 0x3a000000, v255
	v_mul_f32_e32 v129, 0x4b800000, v128
	v_cmp_gt_f32_e32 vcc, s10, v128
	s_nop 1
	v_cndmask_b32_e32 v128, v128, v129, vcc
	v_rsq_f32_e32 v128, v128
	s_nop 0
	v_mul_f32_e32 v129, 0x45800000, v128
	v_cndmask_b32_e32 v130, v128, v129, vcc
	v_lshl_add_u64 v[140:141], v[250:251], 0, s[14:15]
	v_lshlrev_b32_e32 v136, 16, v144
	v_and_b32_e32 v137, 0xffff0000, v144
	v_lshlrev_b32_e32 v138, 16, v145
	v_and_b32_e32 v139, 0xffff0000, v145
	v_pk_mul_f32 v[208:209], v[130:131], v[208:209] op_sel_hi:[0,1]
	v_pk_fma_f32 v[208:209], v[0:1], v[208:209], v[136:137]
	v_pk_mul_f32 v[210:211], v[130:131], v[210:211] op_sel_hi:[0,1]
	v_pk_fma_f32 v[210:211], v[2:3], v[210:211], v[138:139]
	global_store_dwordx4 v[250:251], v[208:211], off offset:0 nt
	v_lshlrev_b32_e32 v136, 16, v146
	v_and_b32_e32 v137, 0xffff0000, v146
	v_lshlrev_b32_e32 v138, 16, v147
	v_and_b32_e32 v139, 0xffff0000, v147
	v_pk_mul_f32 v[212:213], v[130:131], v[212:213] op_sel_hi:[0,1]
	v_pk_fma_f32 v[212:213], v[4:5], v[212:213], v[136:137]
	v_pk_mul_f32 v[214:215], v[130:131], v[214:215] op_sel_hi:[0,1]
	v_pk_fma_f32 v[214:215], v[6:7], v[214:215], v[138:139]
	global_store_dwordx4 v[250:251], v[212:215], off offset:1024 nt
	v_lshlrev_b32_e32 v136, 16, v148
	v_and_b32_e32 v137, 0xffff0000, v148
	v_lshlrev_b32_e32 v138, 16, v149
	v_and_b32_e32 v139, 0xffff0000, v149
	v_pk_mul_f32 v[216:217], v[130:131], v[216:217] op_sel_hi:[0,1]
	v_pk_fma_f32 v[216:217], v[8:9], v[216:217], v[136:137]
	v_pk_mul_f32 v[218:219], v[130:131], v[218:219] op_sel_hi:[0,1]
	v_pk_fma_f32 v[218:219], v[10:11], v[218:219], v[138:139]
	global_store_dwordx4 v[250:251], v[216:219], off offset:2048 nt
	v_lshlrev_b32_e32 v136, 16, v150
	v_and_b32_e32 v137, 0xffff0000, v150
	v_lshlrev_b32_e32 v138, 16, v151
	v_and_b32_e32 v139, 0xffff0000, v151
	v_pk_mul_f32 v[220:221], v[130:131], v[220:221] op_sel_hi:[0,1]
	v_pk_fma_f32 v[220:221], v[12:13], v[220:221], v[136:137]
	v_pk_mul_f32 v[222:223], v[130:131], v[222:223] op_sel_hi:[0,1]
	v_pk_fma_f32 v[222:223], v[14:15], v[222:223], v[138:139]
	global_store_dwordx4 v[250:251], v[220:223], off offset:3072 nt
	v_lshlrev_b32_e32 v136, 16, v152
	v_and_b32_e32 v137, 0xffff0000, v152
	v_lshlrev_b32_e32 v138, 16, v153
	v_and_b32_e32 v139, 0xffff0000, v153
	v_pk_mul_f32 v[224:225], v[130:131], v[224:225] op_sel_hi:[0,1]
	v_pk_fma_f32 v[224:225], v[16:17], v[224:225], v[136:137]
	v_pk_mul_f32 v[226:227], v[130:131], v[226:227] op_sel_hi:[0,1]
	v_pk_fma_f32 v[226:227], v[18:19], v[226:227], v[138:139]
	global_store_dwordx4 v[140:141], v[224:227], off offset:0 nt
	v_lshlrev_b32_e32 v136, 16, v154
	v_and_b32_e32 v137, 0xffff0000, v154
	v_lshlrev_b32_e32 v138, 16, v155
	v_and_b32_e32 v139, 0xffff0000, v155
	v_pk_mul_f32 v[228:229], v[130:131], v[228:229] op_sel_hi:[0,1]
	v_pk_fma_f32 v[228:229], v[20:21], v[228:229], v[136:137]
	v_pk_mul_f32 v[230:231], v[130:131], v[230:231] op_sel_hi:[0,1]
	v_pk_fma_f32 v[230:231], v[22:23], v[230:231], v[138:139]
	global_store_dwordx4 v[140:141], v[228:231], off offset:1024 nt
	v_lshlrev_b32_e32 v136, 16, v156
	v_and_b32_e32 v137, 0xffff0000, v156
	v_lshlrev_b32_e32 v138, 16, v157
	v_and_b32_e32 v139, 0xffff0000, v157
	v_pk_mul_f32 v[232:233], v[130:131], v[232:233] op_sel_hi:[0,1]
	v_pk_fma_f32 v[232:233], v[24:25], v[232:233], v[136:137]
	v_pk_mul_f32 v[234:235], v[130:131], v[234:235] op_sel_hi:[0,1]
	v_pk_fma_f32 v[234:235], v[26:27], v[234:235], v[138:139]
	global_store_dwordx4 v[140:141], v[232:235], off offset:2048 nt
	v_lshlrev_b32_e32 v136, 16, v158
	v_and_b32_e32 v137, 0xffff0000, v158
	v_lshlrev_b32_e32 v138, 16, v159
	v_and_b32_e32 v139, 0xffff0000, v159
	v_pk_mul_f32 v[236:237], v[130:131], v[236:237] op_sel_hi:[0,1]
	v_pk_fma_f32 v[236:237], v[28:29], v[236:237], v[136:137]
	v_pk_mul_f32 v[238:239], v[130:131], v[238:239] op_sel_hi:[0,1]
	v_pk_fma_f32 v[238:239], v[30:31], v[238:239], v[138:139]
	global_store_dwordx4 v[140:141], v[236:239], off offset:3072 nt
	v_lshl_add_u64 v[250:251], v[250:251], 0, s[12:13]
	s_cmpk_gt_i32 s96, 0x1ff
	s_cbranch_scc1 .LBB0_1608
	s_waitcnt vmcnt(16)
	v_lshlrev_b32_e32 v208, 16, v192
	v_and_b32_e32 v209, 0xffff0000, v192
	v_lshlrev_b32_e32 v210, 16, v193
	v_and_b32_e32 v211, 0xffff0000, v193
	v_lshlrev_b32_e32 v212, 16, v194
	v_and_b32_e32 v213, 0xffff0000, v194
	v_lshlrev_b32_e32 v214, 16, v195
	v_and_b32_e32 v215, 0xffff0000, v195
	v_lshlrev_b32_e32 v216, 16, v196
	v_and_b32_e32 v217, 0xffff0000, v196
	v_lshlrev_b32_e32 v218, 16, v197
	v_and_b32_e32 v219, 0xffff0000, v197
	v_lshlrev_b32_e32 v220, 16, v198
	v_and_b32_e32 v221, 0xffff0000, v198
	v_lshlrev_b32_e32 v222, 16, v199
	v_and_b32_e32 v223, 0xffff0000, v199
	v_lshlrev_b32_e32 v224, 16, v200
	v_and_b32_e32 v225, 0xffff0000, v200
	v_lshlrev_b32_e32 v226, 16, v201
	v_and_b32_e32 v227, 0xffff0000, v201
	v_lshlrev_b32_e32 v228, 16, v202
	v_and_b32_e32 v229, 0xffff0000, v202
	v_lshlrev_b32_e32 v230, 16, v203
	v_and_b32_e32 v231, 0xffff0000, v203
	v_lshlrev_b32_e32 v232, 16, v204
	v_and_b32_e32 v233, 0xffff0000, v204
	v_lshlrev_b32_e32 v234, 16, v205
	v_and_b32_e32 v235, 0xffff0000, v205
	v_lshlrev_b32_e32 v236, 16, v206
	v_and_b32_e32 v237, 0xffff0000, v206
	v_lshlrev_b32_e32 v238, 16, v207
	v_and_b32_e32 v239, 0xffff0000, v207
	v_mul_f32_e32 v128, v208, v208
	v_fmac_f32_e32 v128, v209, v209
	v_mul_f32_e32 v129, v210, v210
	v_fmac_f32_e32 v129, v211, v211
	v_add_f32_e32 v128, v128, v129
	v_mul_f32_e32 v129, v212, v212
	v_fmac_f32_e32 v129, v213, v213
	v_mul_f32_e32 v132, v214, v214
	v_fmac_f32_e32 v132, v215, v215
	v_add_f32_e32 v129, v129, v132
	v_add_f32_e32 v128, v128, v129
	v_mul_f32_e32 v129, v216, v216
	v_fmac_f32_e32 v129, v217, v217
	v_mul_f32_e32 v132, v218, v218
	v_fmac_f32_e32 v132, v219, v219
	v_add_f32_e32 v129, v129, v132
	v_add_f32_e32 v128, v128, v129
	v_mul_f32_e32 v129, v220, v220
	v_fmac_f32_e32 v129, v221, v221
	v_mul_f32_e32 v132, v222, v222
	v_fmac_f32_e32 v132, v223, v223
	v_add_f32_e32 v129, v129, v132
	v_add_f32_e32 v128, v128, v129
	v_mul_f32_e32 v129, v224, v224
	v_fmac_f32_e32 v129, v225, v225
	v_mul_f32_e32 v132, v226, v226
	v_fmac_f32_e32 v132, v227, v227
	v_add_f32_e32 v129, v129, v132
	v_add_f32_e32 v128, v128, v129
	v_mul_f32_e32 v129, v228, v228
	v_fmac_f32_e32 v129, v229, v229
	v_mul_f32_e32 v132, v230, v230
	v_fmac_f32_e32 v132, v231, v231
	v_add_f32_e32 v129, v129, v132
	v_add_f32_e32 v128, v128, v129
	v_mul_f32_e32 v129, v232, v232
	v_fmac_f32_e32 v129, v233, v233
	v_mul_f32_e32 v132, v234, v234
	v_fmac_f32_e32 v132, v235, v235
	v_add_f32_e32 v129, v129, v132
	v_add_f32_e32 v128, v128, v129
	v_mul_f32_e32 v129, v236, v236
	v_fmac_f32_e32 v129, v237, v237
	v_mul_f32_e32 v132, v238, v238
	v_fmac_f32_e32 v132, v239, v239
	v_add_f32_e32 v129, v129, v132
	v_add_f32_e32 v128, v128, v129
	ds_bpermute_b32 v129, v244, v128
	s_waitcnt lgkmcnt(0)
	v_add_f32_e32 v128, v128, v129
	ds_bpermute_b32 v129, v245, v128
	s_waitcnt lgkmcnt(0)
	v_add_f32_e32 v128, v128, v129
	ds_bpermute_b32 v129, v246, v128
	s_waitcnt lgkmcnt(0)
	v_add_f32_e32 v128, v128, v129
	ds_bpermute_b32 v129, v247, v128
	s_waitcnt lgkmcnt(0)
	v_add_f32_e32 v128, v128, v129
	ds_bpermute_b32 v129, v248, v128
	s_waitcnt lgkmcnt(0)
	v_add_f32_e32 v128, v128, v129
	ds_bpermute_b32 v129, v249, v128
	s_waitcnt lgkmcnt(0)
	v_add_f32_e32 v128, v128, v129
	v_fmamk_f32 v128, v128, 0x3a000000, v255
	v_mul_f32_e32 v129, 0x4b800000, v128
	v_cmp_gt_f32_e32 vcc, s10, v128
	s_nop 1
	v_cndmask_b32_e32 v128, v128, v129, vcc
	v_rsq_f32_e32 v128, v128
	s_nop 0
	v_mul_f32_e32 v129, 0x45800000, v128
	v_cndmask_b32_e32 v130, v128, v129, vcc
	v_lshl_add_u64 v[140:141], v[250:251], 0, s[14:15]
	v_lshlrev_b32_e32 v136, 16, v176
	v_and_b32_e32 v137, 0xffff0000, v176
	v_lshlrev_b32_e32 v138, 16, v177
	v_and_b32_e32 v139, 0xffff0000, v177
	v_pk_mul_f32 v[208:209], v[130:131], v[208:209] op_sel_hi:[0,1]
	v_pk_fma_f32 v[208:209], v[0:1], v[208:209], v[136:137]
	v_pk_mul_f32 v[210:211], v[130:131], v[210:211] op_sel_hi:[0,1]
	v_pk_fma_f32 v[210:211], v[2:3], v[210:211], v[138:139]
	global_store_dwordx4 v[250:251], v[208:211], off offset:0 nt
	v_lshlrev_b32_e32 v136, 16, v178
	v_and_b32_e32 v137, 0xffff0000, v178
	v_lshlrev_b32_e32 v138, 16, v179
	v_and_b32_e32 v139, 0xffff0000, v179
	v_pk_mul_f32 v[212:213], v[130:131], v[212:213] op_sel_hi:[0,1]
	v_pk_fma_f32 v[212:213], v[4:5], v[212:213], v[136:137]
	v_pk_mul_f32 v[214:215], v[130:131], v[214:215] op_sel_hi:[0,1]
	v_pk_fma_f32 v[214:215], v[6:7], v[214:215], v[138:139]
	global_store_dwordx4 v[250:251], v[212:215], off offset:1024 nt
	v_lshlrev_b32_e32 v136, 16, v180
	v_and_b32_e32 v137, 0xffff0000, v180
	v_lshlrev_b32_e32 v138, 16, v181
	v_and_b32_e32 v139, 0xffff0000, v181
	v_pk_mul_f32 v[216:217], v[130:131], v[216:217] op_sel_hi:[0,1]
	v_pk_fma_f32 v[216:217], v[8:9], v[216:217], v[136:137]
	v_pk_mul_f32 v[218:219], v[130:131], v[218:219] op_sel_hi:[0,1]
	v_pk_fma_f32 v[218:219], v[10:11], v[218:219], v[138:139]
	global_store_dwordx4 v[250:251], v[216:219], off offset:2048 nt
	v_lshlrev_b32_e32 v136, 16, v182
	v_and_b32_e32 v137, 0xffff0000, v182
	v_lshlrev_b32_e32 v138, 16, v183
	v_and_b32_e32 v139, 0xffff0000, v183
	v_pk_mul_f32 v[220:221], v[130:131], v[220:221] op_sel_hi:[0,1]
	v_pk_fma_f32 v[220:221], v[12:13], v[220:221], v[136:137]
	v_pk_mul_f32 v[222:223], v[130:131], v[222:223] op_sel_hi:[0,1]
	v_pk_fma_f32 v[222:223], v[14:15], v[222:223], v[138:139]
	global_store_dwordx4 v[250:251], v[220:223], off offset:3072 nt
	v_lshlrev_b32_e32 v136, 16, v184
	v_and_b32_e32 v137, 0xffff0000, v184
	v_lshlrev_b32_e32 v138, 16, v185
	v_and_b32_e32 v139, 0xffff0000, v185
	v_pk_mul_f32 v[224:225], v[130:131], v[224:225] op_sel_hi:[0,1]
	v_pk_fma_f32 v[224:225], v[16:17], v[224:225], v[136:137]
	v_pk_mul_f32 v[226:227], v[130:131], v[226:227] op_sel_hi:[0,1]
	v_pk_fma_f32 v[226:227], v[18:19], v[226:227], v[138:139]
	global_store_dwordx4 v[140:141], v[224:227], off offset:0 nt
	v_lshlrev_b32_e32 v136, 16, v186
	v_and_b32_e32 v137, 0xffff0000, v186
	v_lshlrev_b32_e32 v138, 16, v187
	v_and_b32_e32 v139, 0xffff0000, v187
	v_pk_mul_f32 v[228:229], v[130:131], v[228:229] op_sel_hi:[0,1]
	v_pk_fma_f32 v[228:229], v[20:21], v[228:229], v[136:137]
	v_pk_mul_f32 v[230:231], v[130:131], v[230:231] op_sel_hi:[0,1]
	v_pk_fma_f32 v[230:231], v[22:23], v[230:231], v[138:139]
	global_store_dwordx4 v[140:141], v[228:231], off offset:1024 nt
	v_lshlrev_b32_e32 v136, 16, v188
	v_and_b32_e32 v137, 0xffff0000, v188
	v_lshlrev_b32_e32 v138, 16, v189
	v_and_b32_e32 v139, 0xffff0000, v189
	v_pk_mul_f32 v[232:233], v[130:131], v[232:233] op_sel_hi:[0,1]
	v_pk_fma_f32 v[232:233], v[24:25], v[232:233], v[136:137]
	v_pk_mul_f32 v[234:235], v[130:131], v[234:235] op_sel_hi:[0,1]
	v_pk_fma_f32 v[234:235], v[26:27], v[234:235], v[138:139]
	global_store_dwordx4 v[140:141], v[232:235], off offset:2048 nt
	v_lshlrev_b32_e32 v136, 16, v190
	v_and_b32_e32 v137, 0xffff0000, v190
	v_lshlrev_b32_e32 v138, 16, v191
	v_and_b32_e32 v139, 0xffff0000, v191
	v_pk_mul_f32 v[236:237], v[130:131], v[236:237] op_sel_hi:[0,1]
	v_pk_fma_f32 v[236:237], v[28:29], v[236:237], v[136:137]
	v_pk_mul_f32 v[238:239], v[130:131], v[238:239] op_sel_hi:[0,1]
	v_pk_fma_f32 v[238:239], v[30:31], v[238:239], v[138:139]
	global_store_dwordx4 v[140:141], v[236:239], off offset:3072 nt
	v_lshl_add_u64 v[250:251], v[250:251], 0, s[12:13]
